# v082 with every s_setprio removed from the GEMM loops (A/B of the per-block priority flips)
# speedup vs baseline: 1.0018x; 1.0018x over previous
; #define PG8_STAGE(bufoff, gbase, voff) do { _Pragma("unroll") for (int _i = 0; _i < 2; ++_i) \
;         __builtin_amdgcn_global_load_lds((const gunsigned*)((const gchar*)(gbase) + (voff)[_i]), (LAS unsigned*)(lds + (bufoff) + ldsw + _i * 8192), 16, 0, 0); } while (0)
; #define PG8_LDA(dst, b, h) do { _Pragma("unroll") for (int m = 0; m < 4; ++m) _Pragma("unroll") for (int k = 0; k < 2; ++k) dst[m][k] = *(const LAS bf16x8*)(lds + PG8_SA(b, h) + aoff + m * 2048 + k * 1024); } while (0)
; #define PG8_LDB(dst, b, h) do { _Pragma("unroll") for (int n = 0; n < 2; ++n) _Pragma("unroll") for (int k = 0; k < 2; ++k) dst[n][k] = *(const LAS bf16x8*)(lds + PG8_SB(b, h) + boff + n * 2048 + k * 1024); } while (0)
; #define PG8_MMA(ai, bj, At, Bt) do { __builtin_amdgcn_s_setprio(1); _Pragma("unroll") for (int m = 0; m < 4; ++m) _Pragma("unroll") for (int n = 0; n < 2; ++n) _Pragma("unroll") for (int k = 0; k < 2; ++k) \
;         acc[ai][bj][m][n] = __builtin_amdgcn_mfma_f32_16x16x32_bf16(Bt[n][k], At[m][k], acc[ai][bj][m][n], 0, 0, 0); __builtin_amdgcn_s_setprio(0); } while (0)
; #define PG8_WAIT_V(n) asm volatile("s_waitcnt vmcnt(" #n ")" ::: "memory")
; #define PG8_WAIT_L(n) asm volatile("s_waitcnt lgkmcnt(" #n ")" ::: "memory")
; #define PG8_BAR __builtin_amdgcn_s_barrier()
; #define PG8_SCHED __builtin_amdgcn_sched_barrier(0)
; template <class Epi, class Sched>
; __device__ __forceinline__ void gemm_phase(LAS unsigned char* lds, const int tid, const Gemm g, const Sched& S, const Epi& E) {
;     ...
;         for (int t = 0; t < nt; t += 2) {
;             const bool last = (t == nt - 2);
;             const gchar* a1 = cA + (size_t)(t + 1) * kstep;
;             const gchar* a2 = last ? nA : cA + (size_t)(t + 2) * kstep; const gchar* b2 = last ? nB : cB + (size_t)(t + 2) * kstep;
;             const gchar* a3 = a2 + kstep; const gchar* b3 = b2 + kstep;
;             PG8_LDB(B0, 0, 0); PG8_LDB(B1, 0, 1); PG8_SCHED; PG8_LDA(At, 0, 0); PG8_STAGE(PG8_SA(1, 1), a1 + hstep, voffA);
;             PG8_WAIT_V(8); PG8_WAIT_L(0); PG8_BAR; PG8_MMA(0, 0, At, B0); PG8_MMA(0, 1, At, B1); PG8_BAR; PG8_SCHED;
;             PG8_LDA(At, 0, 1); PG8_STAGE(PG8_SB(0, 0), b2, voffB); PG8_STAGE(PG8_SB(0, 1), b2 + hstep, voffB); PG8_STAGE(PG8_SA(0, 0), a2, voffA);
;             PG8_WAIT_V(8); PG8_WAIT_L(0); PG8_BAR; PG8_MMA(1, 0, At, B0); PG8_MMA(1, 1, At, B1); PG8_BAR; PG8_SCHED;
.LBB0_319:
	s_add_u32 vcc_lo, s10, 0x100
	s_addc_u32 vcc_hi, s11, 0
	s_add_i32 s39, 0, 0x10000
	s_cmp_eq_u32 s29, 40
	s_cselect_b32 s75, s21, vcc_hi
	s_cselect_b32 s74, s20, vcc_lo
	s_cselect_b32 s73, s1, s93
	s_cselect_b32 s72, s0, s31
	s_add_i32 s30, 0, 0x14000
	v_add_u32_e32 v142, s39, v174
	v_add_u32_e32 v168, s30, v174
	ds_read_b128 v[130:133], v142
	ds_read_b128 v[134:137], v142 offset:1024
	ds_read_b128 v[138:141], v142 offset:2048
	ds_read_b128 v[142:145], v142 offset:3072
	ds_read_b128 v[146:149], v168
	ds_read_b128 v[150:153], v168 offset:1024
	ds_read_b128 v[164:167], v168 offset:2048
	ds_read_b128 v[168:171], v168 offset:3072
	s_add_i32 m0, s46, 0xc000
	ds_read_b128 v[192:195], v190
	ds_read_b128 v[204:207], v190 offset:1024
	ds_read_b128 v[208:211], v190 offset:2048
	ds_read_b128 v[212:215], v190 offset:3072
	ds_read_b128 v[216:219], v190 offset:4096
	ds_read_b128 v[220:223], v190 offset:5120
	ds_read_b128 v[224:227], v190 offset:6144
	ds_read_b128 v[242:245], v190 offset:7168
	global_load_lds_dwordx4 v162, s[10:11]
	s_add_i32 m0, s46, 0xe000
	s_nop 0
	global_load_lds_dwordx4 v160, s[10:11]
	s_waitcnt vmcnt(8)
	s_waitcnt lgkmcnt(0)
	s_barrier
	v_mfma_f32_16x16x32_bf16 v[126:129], v[130:133], v[192:195], v[126:129]
	v_mfma_f32_16x16x32_bf16 v[122:125], v[138:141], v[192:195], v[122:125]
	v_mfma_f32_16x16x32_bf16 v[110:113], v[130:133], v[208:211], v[110:113]
	v_mfma_f32_16x16x32_bf16 v[106:109], v[138:141], v[208:211], v[106:109]
	v_mfma_f32_16x16x32_bf16 v[94:97], v[130:133], v[216:219], v[94:97]
	v_mfma_f32_16x16x32_bf16 v[90:93], v[138:141], v[216:219], v[90:93]
	v_mfma_f32_16x16x32_bf16 v[78:81], v[130:133], v[224:227], v[78:81]
	v_mfma_f32_16x16x32_bf16 v[74:77], v[138:141], v[224:227], v[74:77]
	v_mfma_f32_16x16x32_bf16 v[126:129], v[134:137], v[204:207], v[126:129]
	v_mfma_f32_16x16x32_bf16 v[122:125], v[142:145], v[204:207], v[122:125]
	v_mfma_f32_16x16x32_bf16 v[110:113], v[134:137], v[212:215], v[110:113]
	v_mfma_f32_16x16x32_bf16 v[106:109], v[142:145], v[212:215], v[106:109]
	v_mfma_f32_16x16x32_bf16 v[94:97], v[134:137], v[220:223], v[94:97]
	v_mfma_f32_16x16x32_bf16 v[90:93], v[142:145], v[220:223], v[90:93]
	v_mfma_f32_16x16x32_bf16 v[78:81], v[134:137], v[242:245], v[78:81]
	v_mfma_f32_16x16x32_bf16 v[74:77], v[142:145], v[242:245], v[74:77]
	v_mfma_f32_16x16x32_bf16 v[118:121], v[146:149], v[192:195], v[118:121]
	v_mfma_f32_16x16x32_bf16 v[114:117], v[164:167], v[192:195], v[114:117]
	v_mfma_f32_16x16x32_bf16 v[102:105], v[146:149], v[208:211], v[102:105]
	v_mfma_f32_16x16x32_bf16 v[98:101], v[164:167], v[208:211], v[98:101]
	v_mfma_f32_16x16x32_bf16 v[86:89], v[146:149], v[216:219], v[86:89]
	v_mfma_f32_16x16x32_bf16 v[82:85], v[164:167], v[216:219], v[82:85]
	v_mfma_f32_16x16x32_bf16 v[70:73], v[146:149], v[224:227], v[70:73]
	v_mfma_f32_16x16x32_bf16 v[66:69], v[164:167], v[224:227], v[66:69]
	v_mfma_f32_16x16x32_bf16 v[118:121], v[150:153], v[204:207], v[118:121]
	v_mfma_f32_16x16x32_bf16 v[114:117], v[168:171], v[204:207], v[114:117]
	v_mfma_f32_16x16x32_bf16 v[102:105], v[150:153], v[212:215], v[102:105]
	v_mfma_f32_16x16x32_bf16 v[98:101], v[168:171], v[212:215], v[98:101]
	v_mfma_f32_16x16x32_bf16 v[86:89], v[150:153], v[220:223], v[86:89]
	v_mfma_f32_16x16x32_bf16 v[82:85], v[168:171], v[220:223], v[82:85]
	v_mfma_f32_16x16x32_bf16 v[70:73], v[150:153], v[242:245], v[70:73]
	v_mfma_f32_16x16x32_bf16 v[66:69], v[168:171], v[242:245], v[66:69]
	s_barrier
	s_add_i32 s10, s39, s43
	s_mov_b32 m0, s10
	ds_read_b128 v[192:195], v190 offset:16384
	ds_read_b128 v[204:207], v190 offset:17408
	ds_read_b128 v[208:211], v190 offset:18432
	ds_read_b128 v[212:215], v190 offset:19456
	ds_read_b128 v[216:219], v190 offset:20480
	ds_read_b128 v[220:223], v190 offset:21504
	ds_read_b128 v[224:227], v190 offset:22528
	ds_read_b128 v[242:245], v190 offset:23552
	global_load_lds_dwordx4 v0, s[72:73]
	s_add_i32 m0, s10, 0x2000
	s_add_u32 s10, s72, 0xb0000
	s_addc_u32 s11, s73, 0
	s_add_i32 s30, s30, s43
	global_load_lds_dwordx4 v158, s[72:73]
	s_mov_b32 m0, s30
	s_nop 0
	global_load_lds_dwordx4 v0, s[10:11]
	s_add_i32 m0, s30, 0x2000
	s_nop 0
	global_load_lds_dwordx4 v158, s[10:11]
	s_mov_b32 m0, s46
	s_nop 0
	global_load_lds_dwordx4 v154, s[74:75]
	s_mov_b32 m0, s47
	s_nop 0
	global_load_lds_dwordx4 v156, s[74:75]
	s_waitcnt vmcnt(8)
	s_waitcnt lgkmcnt(0)
	s_barrier
	v_mfma_f32_16x16x32_bf16 v[62:65], v[130:133], v[192:195], v[62:65]
	v_mfma_f32_16x16x32_bf16 v[58:61], v[138:141], v[192:195], v[58:61]
	v_mfma_f32_16x16x32_bf16 v[46:49], v[130:133], v[208:211], v[46:49]
	v_mfma_f32_16x16x32_bf16 v[42:45], v[138:141], v[208:211], v[42:45]
	v_mfma_f32_16x16x32_bf16 v[30:33], v[130:133], v[216:219], v[30:33]
	v_mfma_f32_16x16x32_bf16 v[26:29], v[138:141], v[216:219], v[26:29]
	v_mfma_f32_16x16x32_bf16 v[14:17], v[130:133], v[224:227], v[14:17]
	v_mfma_f32_16x16x32_bf16 v[10:13], v[138:141], v[224:227], v[10:13]
	v_mfma_f32_16x16x32_bf16 v[62:65], v[134:137], v[204:207], v[62:65]
	v_mfma_f32_16x16x32_bf16 v[58:61], v[142:145], v[204:207], v[58:61]
	v_mfma_f32_16x16x32_bf16 v[46:49], v[134:137], v[212:215], v[46:49]
	v_mfma_f32_16x16x32_bf16 v[42:45], v[142:145], v[212:215], v[42:45]
	v_mfma_f32_16x16x32_bf16 v[30:33], v[134:137], v[220:223], v[30:33]
	v_mfma_f32_16x16x32_bf16 v[26:29], v[142:145], v[220:223], v[26:29]
	v_mfma_f32_16x16x32_bf16 v[14:17], v[134:137], v[242:245], v[14:17]
	v_mfma_f32_16x16x32_bf16 v[10:13], v[142:145], v[242:245], v[10:13]
	v_mfma_f32_16x16x32_bf16 v[54:57], v[146:149], v[192:195], v[54:57]
	v_mfma_f32_16x16x32_bf16 v[50:53], v[164:167], v[192:195], v[50:53]
	v_mfma_f32_16x16x32_bf16 v[38:41], v[146:149], v[208:211], v[38:41]
	v_mfma_f32_16x16x32_bf16 v[34:37], v[164:167], v[208:211], v[34:37]
	v_mfma_f32_16x16x32_bf16 v[22:25], v[146:149], v[216:219], v[22:25]
	v_mfma_f32_16x16x32_bf16 v[18:21], v[164:167], v[216:219], v[18:21]
	v_mfma_f32_16x16x32_bf16 v[6:9], v[146:149], v[224:227], v[6:9]
	v_mfma_f32_16x16x32_bf16 v[2:5], v[164:167], v[224:227], v[2:5]
	v_mfma_f32_16x16x32_bf16 v[54:57], v[150:153], v[204:207], v[54:57]
	v_mfma_f32_16x16x32_bf16 v[50:53], v[168:171], v[204:207], v[50:53]
	v_mfma_f32_16x16x32_bf16 v[38:41], v[150:153], v[212:215], v[38:41]
	v_mfma_f32_16x16x32_bf16 v[34:37], v[168:171], v[212:215], v[34:37]
	v_mfma_f32_16x16x32_bf16 v[22:25], v[150:153], v[220:223], v[22:25]
	v_mfma_f32_16x16x32_bf16 v[18:21], v[168:171], v[220:223], v[18:21]
	v_mfma_f32_16x16x32_bf16 v[6:9], v[150:153], v[242:245], v[6:9]
	v_mfma_f32_16x16x32_bf16 v[2:5], v[168:171], v[242:245], v[2:5]
	s_barrier
; #define PG8_STAGE(bufoff, gbase, voff) do { _Pragma("unroll") for (int _i = 0; _i < 2; ++_i) \
;         __builtin_amdgcn_global_load_lds((const gunsigned*)((const gchar*)(gbase) + (voff)[_i]), (LAS unsigned*)(lds + (bufoff) + ldsw + _i * 8192), 16, 0, 0); } while (0)
; #define PG8_LDA(dst, b, h) do { _Pragma("unroll") for (int m = 0; m < 4; ++m) _Pragma("unroll") for (int k = 0; k < 2; ++k) dst[m][k] = *(const LAS bf16x8*)(lds + PG8_SA(b, h) + aoff + m * 2048 + k * 1024); } while (0)
; #define PG8_LDB(dst, b, h) do { _Pragma("unroll") for (int n = 0; n < 2; ++n) _Pragma("unroll") for (int k = 0; k < 2; ++k) dst[n][k] = *(const LAS bf16x8*)(lds + PG8_SB(b, h) + boff + n * 2048 + k * 1024); } while (0)
; #define PG8_MMA(ai, bj, At, Bt) do { __builtin_amdgcn_s_setprio(1); _Pragma("unroll") for (int m = 0; m < 4; ++m) _Pragma("unroll") for (int n = 0; n < 2; ++n) _Pragma("unroll") for (int k = 0; k < 2; ++k) \
;         acc[ai][bj][m][n] = __builtin_amdgcn_mfma_f32_16x16x32_bf16(Bt[n][k], At[m][k], acc[ai][bj][m][n], 0, 0, 0); __builtin_amdgcn_s_setprio(0); } while (0)
; #define PG8_WAIT_V(n) asm volatile("s_waitcnt vmcnt(" #n ")" ::: "memory")
; #define PG8_WAIT_L(n) asm volatile("s_waitcnt lgkmcnt(" #n ")" ::: "memory")
; #define PG8_BAR __builtin_amdgcn_s_barrier()
; #define PG8_SCHED __builtin_amdgcn_sched_barrier(0)
; template <class Epi, class Sched>
; __device__ __forceinline__ void gemm_phase(LAS unsigned char* lds, const int tid, const Gemm g, const Sched& S, const Epi& E) {
;     ...
;             PG8_LDB(B0, 1, 0); PG8_LDB(B1, 1, 1); PG8_SCHED; PG8_LDA(At, 1, 0); PG8_STAGE(PG8_SA(0, 1), a2 + hstep, voffA);
;             PG8_WAIT_V(8); PG8_WAIT_L(0); PG8_BAR; PG8_MMA(0, 0, At, B0); PG8_MMA(0, 1, At, B1); PG8_BAR; PG8_SCHED;
;             PG8_LDA(At, 1, 1); PG8_STAGE(PG8_SB(1, 0), b3, voffB); PG8_STAGE(PG8_SB(1, 1), b3 + hstep, voffB); PG8_STAGE(PG8_SA(1, 0), a3, voffA);
;             PG8_WAIT_V(8); PG8_WAIT_L(0); PG8_BAR; PG8_MMA(1, 0, At, B0); PG8_MMA(1, 1, At, B1); PG8_BAR; PG8_SCHED;
;         }
;         if (wr == 0) PG8_BAR;
	s_add_i32 s30, 0, 0x18000
	s_add_i32 s39, 0, 0x1c000
	v_add_u32_e32 v142, s30, v174
	v_add_u32_e32 v168, s39, v174
	ds_read_b128 v[130:133], v142
	ds_read_b128 v[134:137], v142 offset:1024
	ds_read_b128 v[138:141], v142 offset:2048
	ds_read_b128 v[142:145], v142 offset:3072
	ds_read_b128 v[146:149], v168
	ds_read_b128 v[150:153], v168 offset:1024
	ds_read_b128 v[164:167], v168 offset:2048
	ds_read_b128 v[168:171], v168 offset:3072
	s_add_u32 s10, s74, 0xb0000
	s_addc_u32 s11, s75, 0
	s_mov_b32 m0, s48
	ds_read_b128 v[192:195], v190 offset:32768
	ds_read_b128 v[204:207], v190 offset:33792
	ds_read_b128 v[208:211], v190 offset:34816
	ds_read_b128 v[212:215], v190 offset:35840
	ds_read_b128 v[216:219], v190 offset:36864
	ds_read_b128 v[220:223], v190 offset:37888
	ds_read_b128 v[224:227], v190 offset:38912
	ds_read_b128 v[242:245], v190 offset:39936
	global_load_lds_dwordx4 v154, s[10:11]
	s_mov_b32 m0, s49
	s_nop 0
	global_load_lds_dwordx4 v156, s[10:11]
	s_waitcnt vmcnt(8)
	s_waitcnt lgkmcnt(0)
	s_barrier
	v_mfma_f32_16x16x32_bf16 v[126:129], v[130:133], v[192:195], v[126:129]
	v_mfma_f32_16x16x32_bf16 v[122:125], v[138:141], v[192:195], v[122:125]
	v_mfma_f32_16x16x32_bf16 v[110:113], v[130:133], v[208:211], v[110:113]
	v_mfma_f32_16x16x32_bf16 v[106:109], v[138:141], v[208:211], v[106:109]
	v_mfma_f32_16x16x32_bf16 v[94:97], v[130:133], v[216:219], v[94:97]
	v_mfma_f32_16x16x32_bf16 v[90:93], v[138:141], v[216:219], v[90:93]
	v_mfma_f32_16x16x32_bf16 v[78:81], v[130:133], v[224:227], v[78:81]
	v_mfma_f32_16x16x32_bf16 v[74:77], v[138:141], v[224:227], v[74:77]
	v_mfma_f32_16x16x32_bf16 v[126:129], v[134:137], v[204:207], v[126:129]
	v_mfma_f32_16x16x32_bf16 v[122:125], v[142:145], v[204:207], v[122:125]
	v_mfma_f32_16x16x32_bf16 v[110:113], v[134:137], v[212:215], v[110:113]
	v_mfma_f32_16x16x32_bf16 v[106:109], v[142:145], v[212:215], v[106:109]
	v_mfma_f32_16x16x32_bf16 v[94:97], v[134:137], v[220:223], v[94:97]
	v_mfma_f32_16x16x32_bf16 v[90:93], v[142:145], v[220:223], v[90:93]
	v_mfma_f32_16x16x32_bf16 v[78:81], v[134:137], v[242:245], v[78:81]
	v_mfma_f32_16x16x32_bf16 v[74:77], v[142:145], v[242:245], v[74:77]
	v_mfma_f32_16x16x32_bf16 v[118:121], v[146:149], v[192:195], v[118:121]
	v_mfma_f32_16x16x32_bf16 v[114:117], v[164:167], v[192:195], v[114:117]
	v_mfma_f32_16x16x32_bf16 v[102:105], v[146:149], v[208:211], v[102:105]
	v_mfma_f32_16x16x32_bf16 v[98:101], v[164:167], v[208:211], v[98:101]
	v_mfma_f32_16x16x32_bf16 v[86:89], v[146:149], v[216:219], v[86:89]
	v_mfma_f32_16x16x32_bf16 v[82:85], v[164:167], v[216:219], v[82:85]
	v_mfma_f32_16x16x32_bf16 v[70:73], v[146:149], v[224:227], v[70:73]
	v_mfma_f32_16x16x32_bf16 v[66:69], v[164:167], v[224:227], v[66:69]
	v_mfma_f32_16x16x32_bf16 v[118:121], v[150:153], v[204:207], v[118:121]
	v_mfma_f32_16x16x32_bf16 v[114:117], v[168:171], v[204:207], v[114:117]
	v_mfma_f32_16x16x32_bf16 v[102:105], v[150:153], v[212:215], v[102:105]
	v_mfma_f32_16x16x32_bf16 v[98:101], v[168:171], v[212:215], v[98:101]
	v_mfma_f32_16x16x32_bf16 v[86:89], v[150:153], v[220:223], v[86:89]
	v_mfma_f32_16x16x32_bf16 v[82:85], v[168:171], v[220:223], v[82:85]
	v_mfma_f32_16x16x32_bf16 v[70:73], v[150:153], v[242:245], v[70:73]
	v_mfma_f32_16x16x32_bf16 v[66:69], v[168:171], v[242:245], v[66:69]
	s_barrier
	s_add_i32 s10, s30, s43
	s_mov_b32 m0, s10
	ds_read_b128 v[192:195], v190 offset:49152
	ds_read_b128 v[204:207], v190 offset:50176
	ds_read_b128 v[208:211], v190 offset:51200
	ds_read_b128 v[212:215], v190 offset:52224
	ds_read_b128 v[216:219], v190 offset:53248
	ds_read_b128 v[220:223], v190 offset:54272
	ds_read_b128 v[224:227], v190 offset:55296
	ds_read_b128 v[242:245], v190 offset:56320
	global_load_lds_dwordx4 v201, s[72:73]
	s_add_i32 m0, s10, 0x2000
	s_add_u32 s10, s72, 0xb0080
	s_addc_u32 s11, s73, 0
	s_add_i32 s30, s39, s43
	global_load_lds_dwordx4 v247, s[72:73]
	s_mov_b32 m0, s30
	s_nop 0
	global_load_lds_dwordx4 v0, s[10:11]
	s_add_i32 m0, s30, 0x2000
	s_nop 0
	global_load_lds_dwordx4 v158, s[10:11]
	s_mov_b32 m0, s53
	s_nop 0
	global_load_lds_dwordx4 v249, s[74:75]
	s_mov_b32 m0, s54
	s_nop 0
	global_load_lds_dwordx4 v251, s[74:75]
	s_waitcnt vmcnt(8)
	s_waitcnt lgkmcnt(0)
	s_barrier
	v_mfma_f32_16x16x32_bf16 v[62:65], v[130:133], v[192:195], v[62:65]
	v_mfma_f32_16x16x32_bf16 v[58:61], v[138:141], v[192:195], v[58:61]
	v_mfma_f32_16x16x32_bf16 v[46:49], v[130:133], v[208:211], v[46:49]
	v_mfma_f32_16x16x32_bf16 v[42:45], v[138:141], v[208:211], v[42:45]
	v_mfma_f32_16x16x32_bf16 v[30:33], v[130:133], v[216:219], v[30:33]
	v_mfma_f32_16x16x32_bf16 v[26:29], v[138:141], v[216:219], v[26:29]
	v_mfma_f32_16x16x32_bf16 v[14:17], v[130:133], v[224:227], v[14:17]
	v_mfma_f32_16x16x32_bf16 v[10:13], v[138:141], v[224:227], v[10:13]
	v_mfma_f32_16x16x32_bf16 v[62:65], v[134:137], v[204:207], v[62:65]
	v_mfma_f32_16x16x32_bf16 v[58:61], v[142:145], v[204:207], v[58:61]
	v_mfma_f32_16x16x32_bf16 v[46:49], v[134:137], v[212:215], v[46:49]
	v_mfma_f32_16x16x32_bf16 v[42:45], v[142:145], v[212:215], v[42:45]
	v_mfma_f32_16x16x32_bf16 v[30:33], v[134:137], v[220:223], v[30:33]
	v_mfma_f32_16x16x32_bf16 v[26:29], v[142:145], v[220:223], v[26:29]
	v_mfma_f32_16x16x32_bf16 v[14:17], v[134:137], v[242:245], v[14:17]
	v_mfma_f32_16x16x32_bf16 v[10:13], v[142:145], v[242:245], v[10:13]
	v_mfma_f32_16x16x32_bf16 v[54:57], v[146:149], v[192:195], v[54:57]
	v_mfma_f32_16x16x32_bf16 v[50:53], v[164:167], v[192:195], v[50:53]
	v_mfma_f32_16x16x32_bf16 v[38:41], v[146:149], v[208:211], v[38:41]
	v_mfma_f32_16x16x32_bf16 v[34:37], v[164:167], v[208:211], v[34:37]
	v_mfma_f32_16x16x32_bf16 v[22:25], v[146:149], v[216:219], v[22:25]
	v_mfma_f32_16x16x32_bf16 v[18:21], v[164:167], v[216:219], v[18:21]
	v_mfma_f32_16x16x32_bf16 v[6:9], v[146:149], v[224:227], v[6:9]
	v_mfma_f32_16x16x32_bf16 v[2:5], v[164:167], v[224:227], v[2:5]
	v_mfma_f32_16x16x32_bf16 v[54:57], v[150:153], v[204:207], v[54:57]
	v_mfma_f32_16x16x32_bf16 v[50:53], v[168:171], v[204:207], v[50:53]
	v_mfma_f32_16x16x32_bf16 v[38:41], v[150:153], v[212:215], v[38:41]
	v_mfma_f32_16x16x32_bf16 v[34:37], v[168:171], v[212:215], v[34:37]
	v_mfma_f32_16x16x32_bf16 v[22:25], v[150:153], v[220:223], v[22:25]
	v_mfma_f32_16x16x32_bf16 v[18:21], v[168:171], v[220:223], v[18:21]
	v_mfma_f32_16x16x32_bf16 v[6:9], v[150:153], v[242:245], v[6:9]
	v_mfma_f32_16x16x32_bf16 v[2:5], v[168:171], v[242:245], v[2:5]
	s_barrier
	s_add_i32 s29, s29, 2
	s_add_u32 s31, s31, 0x100
	s_addc_u32 s93, s93, 0
	s_cmp_gt_u32 s29, 41
	s_mov_b64 s[10:11], vcc
	s_cbranch_scc0 .LBB0_319
	s_and_b64 vcc, exec, s[16:17]
	s_cbranch_vccz .LBB0_322
	s_barrier

; #define PG8_STAGE(bufoff, gbase, voff) do { _Pragma("unroll") for (int _i = 0; _i < 2; ++_i) \
;         __builtin_amdgcn_global_load_lds((const gunsigned*)((const gchar*)(gbase) + (voff)[_i]), (LAS unsigned*)(lds + (bufoff) + ldsw + _i * 8192), 16, 0, 0); } while (0)
; #define PG8_LDA(dst, b, h) do { _Pragma("unroll") for (int m = 0; m < 4; ++m) _Pragma("unroll") for (int k = 0; k < 2; ++k) dst[m][k] = *(const LAS bf16x8*)(lds + PG8_SA(b, h) + aoff + m * 2048 + k * 1024); } while (0)
; #define PG8_LDB(dst, b, h) do { _Pragma("unroll") for (int n = 0; n < 2; ++n) _Pragma("unroll") for (int k = 0; k < 2; ++k) dst[n][k] = *(const LAS bf16x8*)(lds + PG8_SB(b, h) + boff + n * 2048 + k * 1024); } while (0)
; #define PG8_MMA(ai, bj, At, Bt) do { __builtin_amdgcn_s_setprio(1); _Pragma("unroll") for (int m = 0; m < 4; ++m) _Pragma("unroll") for (int n = 0; n < 2; ++n) _Pragma("unroll") for (int k = 0; k < 2; ++k) \
;         acc[ai][bj][m][n] = __builtin_amdgcn_mfma_f32_16x16x32_bf16(Bt[n][k], At[m][k], acc[ai][bj][m][n], 0, 0, 0); __builtin_amdgcn_s_setprio(0); } while (0)
; #define PG8_WAIT_V(n) asm volatile("s_waitcnt vmcnt(" #n ")" ::: "memory")
; #define PG8_WAIT_L(n) asm volatile("s_waitcnt lgkmcnt(" #n ")" ::: "memory")
; #define PG8_BAR __builtin_amdgcn_s_barrier()
; #define PG8_SCHED __builtin_amdgcn_sched_barrier(0)
; template <class Epi, class Sched>
; __device__ __forceinline__ void gemm_phase(LAS unsigned char* lds, const int tid, const Gemm g, const Sched& S, const Epi& E) {
;     ...
;         for (int t = 0; t < nt; t += 2) {
;             const bool last = (t == nt - 2);
;             const gchar* a1 = cA + (size_t)(t + 1) * kstep;
;             const gchar* a2 = last ? nA : cA + (size_t)(t + 2) * kstep; const gchar* b2 = last ? nB : cB + (size_t)(t + 2) * kstep;
;             const gchar* a3 = a2 + kstep; const gchar* b3 = b2 + kstep;
;             PG8_LDB(B0, 0, 0); PG8_LDB(B1, 0, 1); PG8_SCHED; PG8_LDA(At, 0, 0); PG8_STAGE(PG8_SA(1, 1), a1 + hstep, voffA);
;             PG8_WAIT_V(8); PG8_WAIT_L(0); PG8_BAR; PG8_MMA(0, 0, At, B0); PG8_MMA(0, 1, At, B1); PG8_BAR; PG8_SCHED;
;             PG8_LDA(At, 0, 1); PG8_STAGE(PG8_SB(0, 0), b2, voffB); PG8_STAGE(PG8_SB(0, 1), b2 + hstep, voffB); PG8_STAGE(PG8_SA(0, 0), a2, voffA);
;             PG8_WAIT_V(8); PG8_WAIT_L(0); PG8_BAR; PG8_MMA(1, 0, At, B0); PG8_MMA(1, 1, At, B1); PG8_BAR; PG8_SCHED;
.LBB0_369:
	s_add_u32 s20, s16, 0xfffc0080
	s_addc_u32 s21, s17, -1
	s_add_i32 s29, 0, 0x10000
	s_cmp_eq_u32 s31, 12
	s_cselect_b32 s57, s11, s21
	s_cselect_b32 s56, s12, s20
	v_add_u32_e32 v140, s29, v145
	s_cselect_b32 s21, s9, s24
	s_cselect_b32 s20, s15, s23
	s_add_i32 s30, 0, 0x14000
	ds_read_b128 v[146:149], v140
	ds_read_b128 v[156:159], v140 offset:1024
	ds_read_b128 v[160:163], v140 offset:2048
	ds_read_b128 v[164:167], v140 offset:3072
	v_add_u32_e32 v140, s30, v145
	ds_read_b128 v[168:171], v140
	ds_read_b128 v[172:175], v140 offset:1024
	ds_read_b128 v[176:179], v140 offset:2048
	ds_read_b128 v[180:183], v140 offset:3072
	s_add_i32 m0, s73, 0xc000
	ds_read_b128 v[184:187], v155
	ds_read_b128 v[188:191], v155 offset:1024
	ds_read_b128 v[192:195], v155 offset:2048
	ds_read_b128 v[204:207], v155 offset:3072
	ds_read_b128 v[208:211], v155 offset:4096
	ds_read_b128 v[212:215], v155 offset:5120
	ds_read_b128 v[216:219], v155 offset:6144
	ds_read_b128 v[220:223], v155 offset:7168
	global_load_lds_dwordx4 v138, s[16:17]
	s_add_i32 m0, s73, 0xe000
	s_nop 0
	global_load_lds_dwordx4 v136, s[16:17]
	s_waitcnt vmcnt(8)
	s_waitcnt lgkmcnt(0)
	s_barrier
	v_mfma_f32_16x16x32_bf16 v[126:129], v[146:149], v[184:187], v[126:129]
	v_mfma_f32_16x16x32_bf16 v[118:121], v[160:163], v[184:187], v[118:121]
	v_mfma_f32_16x16x32_bf16 v[110:113], v[146:149], v[192:195], v[110:113]
	v_mfma_f32_16x16x32_bf16 v[102:105], v[160:163], v[192:195], v[102:105]
	v_mfma_f32_16x16x32_bf16 v[94:97], v[146:149], v[208:211], v[94:97]
	v_mfma_f32_16x16x32_bf16 v[86:89], v[160:163], v[208:211], v[86:89]
	v_mfma_f32_16x16x32_bf16 v[78:81], v[146:149], v[216:219], v[78:81]
	v_mfma_f32_16x16x32_bf16 v[70:73], v[160:163], v[216:219], v[70:73]
	v_mfma_f32_16x16x32_bf16 v[126:129], v[156:159], v[188:191], v[126:129]
	v_mfma_f32_16x16x32_bf16 v[118:121], v[164:167], v[188:191], v[118:121]
	v_mfma_f32_16x16x32_bf16 v[110:113], v[156:159], v[204:207], v[110:113]
	v_mfma_f32_16x16x32_bf16 v[102:105], v[164:167], v[204:207], v[102:105]
	v_mfma_f32_16x16x32_bf16 v[94:97], v[156:159], v[212:215], v[94:97]
	v_mfma_f32_16x16x32_bf16 v[86:89], v[164:167], v[212:215], v[86:89]
	v_mfma_f32_16x16x32_bf16 v[78:81], v[156:159], v[220:223], v[78:81]
	v_mfma_f32_16x16x32_bf16 v[70:73], v[164:167], v[220:223], v[70:73]
	v_mfma_f32_16x16x32_bf16 v[122:125], v[168:171], v[184:187], v[122:125]
	v_mfma_f32_16x16x32_bf16 v[114:117], v[176:179], v[184:187], v[114:117]
	v_mfma_f32_16x16x32_bf16 v[106:109], v[168:171], v[192:195], v[106:109]
	v_mfma_f32_16x16x32_bf16 v[98:101], v[176:179], v[192:195], v[98:101]
	v_mfma_f32_16x16x32_bf16 v[90:93], v[168:171], v[208:211], v[90:93]
	v_mfma_f32_16x16x32_bf16 v[82:85], v[176:179], v[208:211], v[82:85]
	v_mfma_f32_16x16x32_bf16 v[74:77], v[168:171], v[216:219], v[74:77]
	v_mfma_f32_16x16x32_bf16 v[66:69], v[176:179], v[216:219], v[66:69]
	v_mfma_f32_16x16x32_bf16 v[122:125], v[172:175], v[188:191], v[122:125]
	v_mfma_f32_16x16x32_bf16 v[114:117], v[180:183], v[188:191], v[114:117]
	v_mfma_f32_16x16x32_bf16 v[106:109], v[172:175], v[204:207], v[106:109]
	v_mfma_f32_16x16x32_bf16 v[98:101], v[180:183], v[204:207], v[98:101]
	v_mfma_f32_16x16x32_bf16 v[90:93], v[172:175], v[212:215], v[90:93]
	v_mfma_f32_16x16x32_bf16 v[82:85], v[180:183], v[212:215], v[82:85]
	v_mfma_f32_16x16x32_bf16 v[74:77], v[172:175], v[220:223], v[74:77]
	v_mfma_f32_16x16x32_bf16 v[66:69], v[180:183], v[220:223], v[66:69]
	s_barrier
	s_add_i32 s29, s29, s43
	s_mov_b32 m0, s29
	ds_read_b128 v[184:187], v155 offset:16384
	ds_read_b128 v[188:191], v155 offset:17408
	ds_read_b128 v[192:195], v155 offset:18432
	ds_read_b128 v[204:207], v155 offset:19456
	ds_read_b128 v[208:211], v155 offset:20480
	ds_read_b128 v[212:215], v155 offset:21504
	ds_read_b128 v[216:219], v155 offset:22528
	ds_read_b128 v[220:223], v155 offset:23552
	global_load_lds_dwordx4 v0, s[20:21]
	s_add_i32 m0, s29, 0x2000
	s_add_u32 s46, s20, 0x40000
	s_addc_u32 s47, s21, 0
	s_add_i32 s29, s30, s43
	global_load_lds_dwordx4 v130, s[20:21]
	s_mov_b32 m0, s29
	s_nop 0
	global_load_lds_dwordx4 v0, s[46:47]
	s_add_i32 m0, s29, 0x2000
	s_nop 0
	global_load_lds_dwordx4 v130, s[46:47]
	s_mov_b32 m0, s73
	s_nop 0
	global_load_lds_dwordx4 v134, s[56:57]
	s_mov_b32 m0, s74
	s_nop 0
	global_load_lds_dwordx4 v132, s[56:57]
	s_waitcnt vmcnt(8)
	s_waitcnt lgkmcnt(0)
	s_barrier
	v_mfma_f32_16x16x32_bf16 v[62:65], v[146:149], v[184:187], v[62:65]
	v_mfma_f32_16x16x32_bf16 v[54:57], v[160:163], v[184:187], v[54:57]
	v_mfma_f32_16x16x32_bf16 v[46:49], v[146:149], v[192:195], v[46:49]
	v_mfma_f32_16x16x32_bf16 v[38:41], v[160:163], v[192:195], v[38:41]
	v_mfma_f32_16x16x32_bf16 v[30:33], v[146:149], v[208:211], v[30:33]
	v_mfma_f32_16x16x32_bf16 v[22:25], v[160:163], v[208:211], v[22:25]
	v_mfma_f32_16x16x32_bf16 v[14:17], v[146:149], v[216:219], v[14:17]
	v_mfma_f32_16x16x32_bf16 v[6:9], v[160:163], v[216:219], v[6:9]
	v_mfma_f32_16x16x32_bf16 v[62:65], v[156:159], v[188:191], v[62:65]
	v_mfma_f32_16x16x32_bf16 v[54:57], v[164:167], v[188:191], v[54:57]
	v_mfma_f32_16x16x32_bf16 v[46:49], v[156:159], v[204:207], v[46:49]
	v_mfma_f32_16x16x32_bf16 v[38:41], v[164:167], v[204:207], v[38:41]
	v_mfma_f32_16x16x32_bf16 v[30:33], v[156:159], v[212:215], v[30:33]
	v_mfma_f32_16x16x32_bf16 v[22:25], v[164:167], v[212:215], v[22:25]
	v_mfma_f32_16x16x32_bf16 v[14:17], v[156:159], v[220:223], v[14:17]
	v_mfma_f32_16x16x32_bf16 v[6:9], v[164:167], v[220:223], v[6:9]
	v_mfma_f32_16x16x32_bf16 v[58:61], v[168:171], v[184:187], v[58:61]
	v_mfma_f32_16x16x32_bf16 v[50:53], v[176:179], v[184:187], v[50:53]
	v_mfma_f32_16x16x32_bf16 v[42:45], v[168:171], v[192:195], v[42:45]
	v_mfma_f32_16x16x32_bf16 v[34:37], v[176:179], v[192:195], v[34:37]
	v_mfma_f32_16x16x32_bf16 v[26:29], v[168:171], v[208:211], v[26:29]
	v_mfma_f32_16x16x32_bf16 v[18:21], v[176:179], v[208:211], v[18:21]
	v_mfma_f32_16x16x32_bf16 v[10:13], v[168:171], v[216:219], v[10:13]
	v_mfma_f32_16x16x32_bf16 v[2:5], v[176:179], v[216:219], v[2:5]
	v_mfma_f32_16x16x32_bf16 v[58:61], v[172:175], v[188:191], v[58:61]
	v_mfma_f32_16x16x32_bf16 v[50:53], v[180:183], v[188:191], v[50:53]
	v_mfma_f32_16x16x32_bf16 v[42:45], v[172:175], v[204:207], v[42:45]
	v_mfma_f32_16x16x32_bf16 v[34:37], v[180:183], v[204:207], v[34:37]
	v_mfma_f32_16x16x32_bf16 v[26:29], v[172:175], v[212:215], v[26:29]
	v_mfma_f32_16x16x32_bf16 v[18:21], v[180:183], v[212:215], v[18:21]
	v_mfma_f32_16x16x32_bf16 v[10:13], v[172:175], v[220:223], v[10:13]
	v_mfma_f32_16x16x32_bf16 v[2:5], v[180:183], v[220:223], v[2:5]
	s_barrier
; #define PG8_STAGE(bufoff, gbase, voff) do { _Pragma("unroll") for (int _i = 0; _i < 2; ++_i) \
;         __builtin_amdgcn_global_load_lds((const gunsigned*)((const gchar*)(gbase) + (voff)[_i]), (LAS unsigned*)(lds + (bufoff) + ldsw + _i * 8192), 16, 0, 0); } while (0)
; #define PG8_LDA(dst, b, h) do { _Pragma("unroll") for (int m = 0; m < 4; ++m) _Pragma("unroll") for (int k = 0; k < 2; ++k) dst[m][k] = *(const LAS bf16x8*)(lds + PG8_SA(b, h) + aoff + m * 2048 + k * 1024); } while (0)
; #define PG8_LDB(dst, b, h) do { _Pragma("unroll") for (int n = 0; n < 2; ++n) _Pragma("unroll") for (int k = 0; k < 2; ++k) dst[n][k] = *(const LAS bf16x8*)(lds + PG8_SB(b, h) + boff + n * 2048 + k * 1024); } while (0)
; #define PG8_MMA(ai, bj, At, Bt) do { __builtin_amdgcn_s_setprio(1); _Pragma("unroll") for (int m = 0; m < 4; ++m) _Pragma("unroll") for (int n = 0; n < 2; ++n) _Pragma("unroll") for (int k = 0; k < 2; ++k) \
;         acc[ai][bj][m][n] = __builtin_amdgcn_mfma_f32_16x16x32_bf16(Bt[n][k], At[m][k], acc[ai][bj][m][n], 0, 0, 0); __builtin_amdgcn_s_setprio(0); } while (0)
; #define PG8_WAIT_V(n) asm volatile("s_waitcnt vmcnt(" #n ")" ::: "memory")
; #define PG8_WAIT_L(n) asm volatile("s_waitcnt lgkmcnt(" #n ")" ::: "memory")
; #define PG8_BAR __builtin_amdgcn_s_barrier()
; #define PG8_SCHED __builtin_amdgcn_sched_barrier(0)
; template <class Epi, class Sched>
; __device__ __forceinline__ void gemm_phase(LAS unsigned char* lds, const int tid, const Gemm g, const Sched& S, const Epi& E) {
;     ...
;             PG8_LDB(B0, 1, 0); PG8_LDB(B1, 1, 1); PG8_SCHED; PG8_LDA(At, 1, 0); PG8_STAGE(PG8_SA(0, 1), a2 + hstep, voffA);
;             PG8_WAIT_V(8); PG8_WAIT_L(0); PG8_BAR; PG8_MMA(0, 0, At, B0); PG8_MMA(0, 1, At, B1); PG8_BAR; PG8_SCHED;
;             PG8_LDA(At, 1, 1); PG8_STAGE(PG8_SB(1, 0), b3, voffB); PG8_STAGE(PG8_SB(1, 1), b3 + hstep, voffB); PG8_STAGE(PG8_SA(1, 0), a3, voffA);
;             PG8_WAIT_V(8); PG8_WAIT_L(0); PG8_BAR; PG8_MMA(1, 0, At, B0); PG8_MMA(1, 1, At, B1); PG8_BAR; PG8_SCHED;
;         }
;         if (wr == 0) PG8_BAR;
	s_add_i32 s29, 0, 0x18000
	v_add_u32_e32 v142, s29, v145
	s_add_i32 s30, 0, 0x1c000
	ds_read_b128 v[146:149], v142
	ds_read_b128 v[156:159], v142 offset:1024
	ds_read_b128 v[160:163], v142 offset:2048
	ds_read_b128 v[164:167], v142 offset:3072
	v_add_u32_e32 v142, s30, v145
	ds_read_b128 v[168:171], v142
	ds_read_b128 v[172:175], v142 offset:1024
	ds_read_b128 v[176:179], v142 offset:2048
	ds_read_b128 v[180:183], v142 offset:3072
	s_add_u32 s46, s56, 0x40000
	s_addc_u32 s47, s57, 0
	s_mov_b32 m0, s75
	ds_read_b128 v[184:187], v155 offset:32768
	ds_read_b128 v[188:191], v155 offset:33792
	ds_read_b128 v[192:195], v155 offset:34816
	ds_read_b128 v[204:207], v155 offset:35840
	ds_read_b128 v[208:211], v155 offset:36864
	ds_read_b128 v[212:215], v155 offset:37888
	ds_read_b128 v[216:219], v155 offset:38912
	ds_read_b128 v[220:223], v155 offset:39936
	global_load_lds_dwordx4 v134, s[46:47]
	s_mov_b32 m0, s92
	s_nop 0
	global_load_lds_dwordx4 v132, s[46:47]
	s_waitcnt vmcnt(8)
	s_waitcnt lgkmcnt(0)
	s_barrier
	v_mfma_f32_16x16x32_bf16 v[126:129], v[146:149], v[184:187], v[126:129]
	v_mfma_f32_16x16x32_bf16 v[118:121], v[160:163], v[184:187], v[118:121]
	v_mfma_f32_16x16x32_bf16 v[110:113], v[146:149], v[192:195], v[110:113]
	v_mfma_f32_16x16x32_bf16 v[102:105], v[160:163], v[192:195], v[102:105]
	v_mfma_f32_16x16x32_bf16 v[94:97], v[146:149], v[208:211], v[94:97]
	v_mfma_f32_16x16x32_bf16 v[86:89], v[160:163], v[208:211], v[86:89]
	v_mfma_f32_16x16x32_bf16 v[78:81], v[146:149], v[216:219], v[78:81]
	v_mfma_f32_16x16x32_bf16 v[70:73], v[160:163], v[216:219], v[70:73]
	v_mfma_f32_16x16x32_bf16 v[126:129], v[156:159], v[188:191], v[126:129]
	v_mfma_f32_16x16x32_bf16 v[118:121], v[164:167], v[188:191], v[118:121]
	v_mfma_f32_16x16x32_bf16 v[110:113], v[156:159], v[204:207], v[110:113]
	v_mfma_f32_16x16x32_bf16 v[102:105], v[164:167], v[204:207], v[102:105]
	v_mfma_f32_16x16x32_bf16 v[94:97], v[156:159], v[212:215], v[94:97]
	v_mfma_f32_16x16x32_bf16 v[86:89], v[164:167], v[212:215], v[86:89]
	v_mfma_f32_16x16x32_bf16 v[78:81], v[156:159], v[220:223], v[78:81]
	v_mfma_f32_16x16x32_bf16 v[70:73], v[164:167], v[220:223], v[70:73]
	v_mfma_f32_16x16x32_bf16 v[122:125], v[168:171], v[184:187], v[122:125]
	v_mfma_f32_16x16x32_bf16 v[114:117], v[176:179], v[184:187], v[114:117]
	v_mfma_f32_16x16x32_bf16 v[106:109], v[168:171], v[192:195], v[106:109]
	v_mfma_f32_16x16x32_bf16 v[98:101], v[176:179], v[192:195], v[98:101]
	v_mfma_f32_16x16x32_bf16 v[90:93], v[168:171], v[208:211], v[90:93]
	v_mfma_f32_16x16x32_bf16 v[82:85], v[176:179], v[208:211], v[82:85]
	v_mfma_f32_16x16x32_bf16 v[74:77], v[168:171], v[216:219], v[74:77]
	v_mfma_f32_16x16x32_bf16 v[66:69], v[176:179], v[216:219], v[66:69]
	v_mfma_f32_16x16x32_bf16 v[122:125], v[172:175], v[188:191], v[122:125]
	v_mfma_f32_16x16x32_bf16 v[114:117], v[180:183], v[188:191], v[114:117]
	v_mfma_f32_16x16x32_bf16 v[106:109], v[172:175], v[204:207], v[106:109]
	v_mfma_f32_16x16x32_bf16 v[98:101], v[180:183], v[204:207], v[98:101]
	v_mfma_f32_16x16x32_bf16 v[90:93], v[172:175], v[212:215], v[90:93]
	v_mfma_f32_16x16x32_bf16 v[82:85], v[180:183], v[212:215], v[82:85]
	v_mfma_f32_16x16x32_bf16 v[74:77], v[172:175], v[220:223], v[74:77]
	v_mfma_f32_16x16x32_bf16 v[66:69], v[180:183], v[220:223], v[66:69]
	s_barrier
	s_add_i32 s29, s29, s43
	s_mov_b32 m0, s29
	ds_read_b128 v[184:187], v155 offset:49152
	ds_read_b128 v[188:191], v155 offset:50176
	ds_read_b128 v[192:195], v155 offset:51200
	ds_read_b128 v[204:207], v155 offset:52224
	ds_read_b128 v[208:211], v155 offset:53248
	ds_read_b128 v[212:215], v155 offset:54272
	ds_read_b128 v[216:219], v155 offset:55296
	ds_read_b128 v[220:223], v155 offset:56320
	global_load_lds_dwordx4 v141, s[20:21]
	s_add_i32 m0, s29, 0x2000
	s_add_i32 s29, s30, s43
	global_load_lds_dwordx4 v153, s[20:21]
	s_add_u32 s20, s20, 0x40080
	s_addc_u32 s21, s21, 0
	s_mov_b32 m0, s29
	s_nop 0
	global_load_lds_dwordx4 v0, s[20:21]
	s_add_i32 m0, s29, 0x2000
	s_nop 0
	global_load_lds_dwordx4 v130, s[20:21]
	s_mov_b32 m0, s93
	s_nop 0
	global_load_lds_dwordx4 v201, s[56:57]
	s_mov_b32 m0, s44
	s_nop 0
	global_load_lds_dwordx4 v225, s[56:57]
	s_waitcnt vmcnt(8)
	s_waitcnt lgkmcnt(0)
	s_barrier
	v_mfma_f32_16x16x32_bf16 v[62:65], v[146:149], v[184:187], v[62:65]
	v_mfma_f32_16x16x32_bf16 v[54:57], v[160:163], v[184:187], v[54:57]
	v_mfma_f32_16x16x32_bf16 v[46:49], v[146:149], v[192:195], v[46:49]
	v_mfma_f32_16x16x32_bf16 v[38:41], v[160:163], v[192:195], v[38:41]
	v_mfma_f32_16x16x32_bf16 v[30:33], v[146:149], v[208:211], v[30:33]
	v_mfma_f32_16x16x32_bf16 v[22:25], v[160:163], v[208:211], v[22:25]
	v_mfma_f32_16x16x32_bf16 v[14:17], v[146:149], v[216:219], v[14:17]
	v_mfma_f32_16x16x32_bf16 v[6:9], v[160:163], v[216:219], v[6:9]
	v_mfma_f32_16x16x32_bf16 v[62:65], v[156:159], v[188:191], v[62:65]
	v_mfma_f32_16x16x32_bf16 v[54:57], v[164:167], v[188:191], v[54:57]
	v_mfma_f32_16x16x32_bf16 v[46:49], v[156:159], v[204:207], v[46:49]
	v_mfma_f32_16x16x32_bf16 v[38:41], v[164:167], v[204:207], v[38:41]
	v_mfma_f32_16x16x32_bf16 v[30:33], v[156:159], v[212:215], v[30:33]
	v_mfma_f32_16x16x32_bf16 v[22:25], v[164:167], v[212:215], v[22:25]
	v_mfma_f32_16x16x32_bf16 v[14:17], v[156:159], v[220:223], v[14:17]
	v_mfma_f32_16x16x32_bf16 v[6:9], v[164:167], v[220:223], v[6:9]
	v_mfma_f32_16x16x32_bf16 v[58:61], v[168:171], v[184:187], v[58:61]
	v_mfma_f32_16x16x32_bf16 v[50:53], v[176:179], v[184:187], v[50:53]
	v_mfma_f32_16x16x32_bf16 v[42:45], v[168:171], v[192:195], v[42:45]
	v_mfma_f32_16x16x32_bf16 v[34:37], v[176:179], v[192:195], v[34:37]
	v_mfma_f32_16x16x32_bf16 v[26:29], v[168:171], v[208:211], v[26:29]
	v_mfma_f32_16x16x32_bf16 v[18:21], v[176:179], v[208:211], v[18:21]
	v_mfma_f32_16x16x32_bf16 v[10:13], v[168:171], v[216:219], v[10:13]
	v_mfma_f32_16x16x32_bf16 v[2:5], v[176:179], v[216:219], v[2:5]
	v_mfma_f32_16x16x32_bf16 v[58:61], v[172:175], v[188:191], v[58:61]
	v_mfma_f32_16x16x32_bf16 v[50:53], v[180:183], v[188:191], v[50:53]
	v_mfma_f32_16x16x32_bf16 v[42:45], v[172:175], v[204:207], v[42:45]
	v_mfma_f32_16x16x32_bf16 v[34:37], v[180:183], v[204:207], v[34:37]
	v_mfma_f32_16x16x32_bf16 v[26:29], v[172:175], v[212:215], v[26:29]
	v_mfma_f32_16x16x32_bf16 v[18:21], v[180:183], v[212:215], v[18:21]
	v_mfma_f32_16x16x32_bf16 v[10:13], v[172:175], v[220:223], v[10:13]
	v_mfma_f32_16x16x32_bf16 v[2:5], v[180:183], v[220:223], v[2:5]
	s_barrier
	s_add_i32 s31, s31, 2
	s_add_u32 s23, s23, 0x100
	s_addc_u32 s24, s24, 0
	s_add_u32 s16, s16, 0x100
	s_addc_u32 s17, s17, 0
	s_cmp_gt_u32 s31, 13
	s_cbranch_scc0 .LBB0_369
	s_and_b64 vcc, exec, s[6:7]
	s_cbranch_vccz .LBB0_372
	s_barrier

; #define PG8_STAGE(bufoff, gbase, voff) do { _Pragma("unroll") for (int _i = 0; _i < 2; ++_i) \
;         __builtin_amdgcn_global_load_lds((const gunsigned*)((const gchar*)(gbase) + (voff)[_i]), (LAS unsigned*)(lds + (bufoff) + ldsw + _i * 8192), 16, 0, 0); } while (0)
; #define PG8_LDA(dst, b, h) do { _Pragma("unroll") for (int m = 0; m < 4; ++m) _Pragma("unroll") for (int k = 0; k < 2; ++k) dst[m][k] = *(const LAS bf16x8*)(lds + PG8_SA(b, h) + aoff + m * 2048 + k * 1024); } while (0)
; #define PG8_LDB(dst, b, h) do { _Pragma("unroll") for (int n = 0; n < 2; ++n) _Pragma("unroll") for (int k = 0; k < 2; ++k) dst[n][k] = *(const LAS bf16x8*)(lds + PG8_SB(b, h) + boff + n * 2048 + k * 1024); } while (0)
; #define PG8_MMA(ai, bj, At, Bt) do { __builtin_amdgcn_s_setprio(1); _Pragma("unroll") for (int m = 0; m < 4; ++m) _Pragma("unroll") for (int n = 0; n < 2; ++n) _Pragma("unroll") for (int k = 0; k < 2; ++k) \
;         acc[ai][bj][m][n] = __builtin_amdgcn_mfma_f32_16x16x32_bf16(Bt[n][k], At[m][k], acc[ai][bj][m][n], 0, 0, 0); __builtin_amdgcn_s_setprio(0); } while (0)
; #define PG8_WAIT_V(n) asm volatile("s_waitcnt vmcnt(" #n ")" ::: "memory")
; #define PG8_WAIT_L(n) asm volatile("s_waitcnt lgkmcnt(" #n ")" ::: "memory")
; #define PG8_BAR __builtin_amdgcn_s_barrier()
; #define PG8_SCHED __builtin_amdgcn_sched_barrier(0)
; template <class Epi, class Sched>
; __device__ __forceinline__ void gemm_phase(LAS unsigned char* lds, const int tid, const Gemm g, const Sched& S, const Epi& E) {
;     ...
;         for (int t = 0; t < nt; t += 2) {
;             const bool last = (t == nt - 2);
;             const gchar* a1 = cA + (size_t)(t + 1) * kstep;
;             const gchar* a2 = last ? nA : cA + (size_t)(t + 2) * kstep; const gchar* b2 = last ? nB : cB + (size_t)(t + 2) * kstep;
;             const gchar* a3 = a2 + kstep; const gchar* b3 = b2 + kstep;
;             PG8_LDB(B0, 0, 0); PG8_LDB(B1, 0, 1); PG8_SCHED; PG8_LDA(At, 0, 0); PG8_STAGE(PG8_SA(1, 1), a1 + hstep, voffA);
;             PG8_WAIT_V(8); PG8_WAIT_L(0); PG8_BAR; PG8_MMA(0, 0, At, B0); PG8_MMA(0, 1, At, B1); PG8_BAR; PG8_SCHED;
;             PG8_LDA(At, 0, 1); PG8_STAGE(PG8_SB(0, 0), b2, voffB); PG8_STAGE(PG8_SB(0, 1), b2 + hstep, voffB); PG8_STAGE(PG8_SA(0, 0), a2, voffA);
;             PG8_WAIT_V(8); PG8_WAIT_L(0); PG8_BAR; PG8_MMA(1, 0, At, B0); PG8_MMA(1, 1, At, B1); PG8_BAR; PG8_SCHED;
.LBB0_397:
	s_add_u32 s20, s92, 0xfffc0080
	s_addc_u32 s21, s93, -1
	s_add_i32 s29, 0, 0x10000
	s_cmp_eq_u32 s53, 12
	s_cselect_b32 s73, s1, s21
	s_cselect_b32 s72, s31, s20
	s_cselect_b32 s21, s17, s52
	s_cselect_b32 s20, s50, s51
	s_add_i32 s30, 0, 0x14000
	v_add_u32_e32 v142, s29, v177
	v_add_u32_e32 v168, s30, v177
	ds_read_b128 v[130:133], v142
	ds_read_b128 v[134:137], v142 offset:1024
	ds_read_b128 v[138:141], v142 offset:2048
	ds_read_b128 v[142:145], v142 offset:3072
	ds_read_b128 v[146:149], v168
	ds_read_b128 v[150:153], v168 offset:1024
	ds_read_b128 v[164:167], v168 offset:2048
	ds_read_b128 v[168:171], v168 offset:3072
	s_add_i32 m0, s43, 0xc000
	ds_read_b128 v[172:175], v181
	ds_read_b128 v[182:185], v181 offset:1024
	ds_read_b128 v[186:189], v181 offset:2048
	ds_read_b128 v[190:193], v181 offset:3072
	ds_read_b128 v[204:207], v181 offset:4096
	ds_read_b128 v[208:211], v181 offset:5120
	ds_read_b128 v[212:215], v181 offset:6144
	ds_read_b128 v[216:219], v181 offset:7168
	global_load_lds_dwordx4 v162, s[92:93]
	s_add_i32 m0, s43, 0xe000
	s_nop 0
	global_load_lds_dwordx4 v160, s[92:93]
	s_waitcnt vmcnt(8)
	s_waitcnt lgkmcnt(0)
	s_barrier
	v_mfma_f32_16x16x32_bf16 v[126:129], v[130:133], v[172:175], v[126:129]
	v_mfma_f32_16x16x32_bf16 v[122:125], v[138:141], v[172:175], v[122:125]
	v_mfma_f32_16x16x32_bf16 v[110:113], v[130:133], v[186:189], v[110:113]
	v_mfma_f32_16x16x32_bf16 v[106:109], v[138:141], v[186:189], v[106:109]
	v_mfma_f32_16x16x32_bf16 v[94:97], v[130:133], v[204:207], v[94:97]
	v_mfma_f32_16x16x32_bf16 v[90:93], v[138:141], v[204:207], v[90:93]
	v_mfma_f32_16x16x32_bf16 v[78:81], v[130:133], v[212:215], v[78:81]
	v_mfma_f32_16x16x32_bf16 v[74:77], v[138:141], v[212:215], v[74:77]
	v_mfma_f32_16x16x32_bf16 v[126:129], v[134:137], v[182:185], v[126:129]
	v_mfma_f32_16x16x32_bf16 v[122:125], v[142:145], v[182:185], v[122:125]
	v_mfma_f32_16x16x32_bf16 v[110:113], v[134:137], v[190:193], v[110:113]
	v_mfma_f32_16x16x32_bf16 v[106:109], v[142:145], v[190:193], v[106:109]
	v_mfma_f32_16x16x32_bf16 v[94:97], v[134:137], v[208:211], v[94:97]
	v_mfma_f32_16x16x32_bf16 v[90:93], v[142:145], v[208:211], v[90:93]
	v_mfma_f32_16x16x32_bf16 v[78:81], v[134:137], v[216:219], v[78:81]
	v_mfma_f32_16x16x32_bf16 v[74:77], v[142:145], v[216:219], v[74:77]
	v_mfma_f32_16x16x32_bf16 v[118:121], v[146:149], v[172:175], v[118:121]
	v_mfma_f32_16x16x32_bf16 v[114:117], v[164:167], v[172:175], v[114:117]
	v_mfma_f32_16x16x32_bf16 v[102:105], v[146:149], v[186:189], v[102:105]
	v_mfma_f32_16x16x32_bf16 v[98:101], v[164:167], v[186:189], v[98:101]
	v_mfma_f32_16x16x32_bf16 v[86:89], v[146:149], v[204:207], v[86:89]
	v_mfma_f32_16x16x32_bf16 v[82:85], v[164:167], v[204:207], v[82:85]
	v_mfma_f32_16x16x32_bf16 v[70:73], v[146:149], v[212:215], v[70:73]
	v_mfma_f32_16x16x32_bf16 v[66:69], v[164:167], v[212:215], v[66:69]
	v_mfma_f32_16x16x32_bf16 v[118:121], v[150:153], v[182:185], v[118:121]
	v_mfma_f32_16x16x32_bf16 v[114:117], v[168:171], v[182:185], v[114:117]
	v_mfma_f32_16x16x32_bf16 v[102:105], v[150:153], v[190:193], v[102:105]
	v_mfma_f32_16x16x32_bf16 v[98:101], v[168:171], v[190:193], v[98:101]
	v_mfma_f32_16x16x32_bf16 v[86:89], v[150:153], v[208:211], v[86:89]
	v_mfma_f32_16x16x32_bf16 v[82:85], v[168:171], v[208:211], v[82:85]
	v_mfma_f32_16x16x32_bf16 v[70:73], v[150:153], v[216:219], v[70:73]
	v_mfma_f32_16x16x32_bf16 v[66:69], v[168:171], v[216:219], v[66:69]
	s_barrier
	s_add_i32 s29, s29, s15
	s_mov_b32 m0, s29
	ds_read_b128 v[172:175], v181 offset:16384
	ds_read_b128 v[182:185], v181 offset:17408
	ds_read_b128 v[186:189], v181 offset:18432
	ds_read_b128 v[190:193], v181 offset:19456
	ds_read_b128 v[204:207], v181 offset:20480
	ds_read_b128 v[208:211], v181 offset:21504
	ds_read_b128 v[212:215], v181 offset:22528
	ds_read_b128 v[216:219], v181 offset:23552
	global_load_lds_dwordx4 v0, s[20:21]
	s_add_i32 m0, s29, 0x2000
	s_add_u32 s54, s20, 0x40000
	s_addc_u32 s55, s21, 0
	s_add_i32 s29, s30, s15
	global_load_lds_dwordx4 v158, s[20:21]
	s_mov_b32 m0, s29
	s_nop 0
	global_load_lds_dwordx4 v0, s[54:55]
	s_add_i32 m0, s29, 0x2000
	s_nop 0
	global_load_lds_dwordx4 v158, s[54:55]
	s_mov_b32 m0, s43
	s_nop 0
	global_load_lds_dwordx4 v154, s[72:73]
	s_mov_b32 m0, s44
	s_nop 0
	global_load_lds_dwordx4 v156, s[72:73]
	s_waitcnt vmcnt(8)
	s_waitcnt lgkmcnt(0)
	s_barrier
	v_mfma_f32_16x16x32_bf16 v[62:65], v[130:133], v[172:175], v[62:65]
	v_mfma_f32_16x16x32_bf16 v[58:61], v[138:141], v[172:175], v[58:61]
	v_mfma_f32_16x16x32_bf16 v[46:49], v[130:133], v[186:189], v[46:49]
	v_mfma_f32_16x16x32_bf16 v[42:45], v[138:141], v[186:189], v[42:45]
	v_mfma_f32_16x16x32_bf16 v[30:33], v[130:133], v[204:207], v[30:33]
	v_mfma_f32_16x16x32_bf16 v[26:29], v[138:141], v[204:207], v[26:29]
	v_mfma_f32_16x16x32_bf16 v[14:17], v[130:133], v[212:215], v[14:17]
	v_mfma_f32_16x16x32_bf16 v[10:13], v[138:141], v[212:215], v[10:13]
	v_mfma_f32_16x16x32_bf16 v[62:65], v[134:137], v[182:185], v[62:65]
	v_mfma_f32_16x16x32_bf16 v[58:61], v[142:145], v[182:185], v[58:61]
	v_mfma_f32_16x16x32_bf16 v[46:49], v[134:137], v[190:193], v[46:49]
	v_mfma_f32_16x16x32_bf16 v[42:45], v[142:145], v[190:193], v[42:45]
	v_mfma_f32_16x16x32_bf16 v[30:33], v[134:137], v[208:211], v[30:33]
	v_mfma_f32_16x16x32_bf16 v[26:29], v[142:145], v[208:211], v[26:29]
	v_mfma_f32_16x16x32_bf16 v[14:17], v[134:137], v[216:219], v[14:17]
	v_mfma_f32_16x16x32_bf16 v[10:13], v[142:145], v[216:219], v[10:13]
	v_mfma_f32_16x16x32_bf16 v[54:57], v[146:149], v[172:175], v[54:57]
	v_mfma_f32_16x16x32_bf16 v[50:53], v[164:167], v[172:175], v[50:53]
	v_mfma_f32_16x16x32_bf16 v[38:41], v[146:149], v[186:189], v[38:41]
	v_mfma_f32_16x16x32_bf16 v[34:37], v[164:167], v[186:189], v[34:37]
	v_mfma_f32_16x16x32_bf16 v[22:25], v[146:149], v[204:207], v[22:25]
	v_mfma_f32_16x16x32_bf16 v[18:21], v[164:167], v[204:207], v[18:21]
	v_mfma_f32_16x16x32_bf16 v[6:9], v[146:149], v[212:215], v[6:9]
	v_mfma_f32_16x16x32_bf16 v[2:5], v[164:167], v[212:215], v[2:5]
	v_mfma_f32_16x16x32_bf16 v[54:57], v[150:153], v[182:185], v[54:57]
	v_mfma_f32_16x16x32_bf16 v[50:53], v[168:171], v[182:185], v[50:53]
	v_mfma_f32_16x16x32_bf16 v[38:41], v[150:153], v[190:193], v[38:41]
	v_mfma_f32_16x16x32_bf16 v[34:37], v[168:171], v[190:193], v[34:37]
	v_mfma_f32_16x16x32_bf16 v[22:25], v[150:153], v[208:211], v[22:25]
	v_mfma_f32_16x16x32_bf16 v[18:21], v[168:171], v[208:211], v[18:21]
	v_mfma_f32_16x16x32_bf16 v[6:9], v[150:153], v[216:219], v[6:9]
	v_mfma_f32_16x16x32_bf16 v[2:5], v[168:171], v[216:219], v[2:5]
	s_barrier
; #define PG8_STAGE(bufoff, gbase, voff) do { _Pragma("unroll") for (int _i = 0; _i < 2; ++_i) \
;         __builtin_amdgcn_global_load_lds((const gunsigned*)((const gchar*)(gbase) + (voff)[_i]), (LAS unsigned*)(lds + (bufoff) + ldsw + _i * 8192), 16, 0, 0); } while (0)
; #define PG8_LDA(dst, b, h) do { _Pragma("unroll") for (int m = 0; m < 4; ++m) _Pragma("unroll") for (int k = 0; k < 2; ++k) dst[m][k] = *(const LAS bf16x8*)(lds + PG8_SA(b, h) + aoff + m * 2048 + k * 1024); } while (0)
; #define PG8_LDB(dst, b, h) do { _Pragma("unroll") for (int n = 0; n < 2; ++n) _Pragma("unroll") for (int k = 0; k < 2; ++k) dst[n][k] = *(const LAS bf16x8*)(lds + PG8_SB(b, h) + boff + n * 2048 + k * 1024); } while (0)
; #define PG8_MMA(ai, bj, At, Bt) do { __builtin_amdgcn_s_setprio(1); _Pragma("unroll") for (int m = 0; m < 4; ++m) _Pragma("unroll") for (int n = 0; n < 2; ++n) _Pragma("unroll") for (int k = 0; k < 2; ++k) \
;         acc[ai][bj][m][n] = __builtin_amdgcn_mfma_f32_16x16x32_bf16(Bt[n][k], At[m][k], acc[ai][bj][m][n], 0, 0, 0); __builtin_amdgcn_s_setprio(0); } while (0)
; #define PG8_WAIT_V(n) asm volatile("s_waitcnt vmcnt(" #n ")" ::: "memory")
; #define PG8_WAIT_L(n) asm volatile("s_waitcnt lgkmcnt(" #n ")" ::: "memory")
; #define PG8_BAR __builtin_amdgcn_s_barrier()
; #define PG8_SCHED __builtin_amdgcn_sched_barrier(0)
; template <class Epi, class Sched>
; __device__ __forceinline__ void gemm_phase(LAS unsigned char* lds, const int tid, const Gemm g, const Sched& S, const Epi& E) {
;     ...
;             PG8_LDB(B0, 1, 0); PG8_LDB(B1, 1, 1); PG8_SCHED; PG8_LDA(At, 1, 0); PG8_STAGE(PG8_SA(0, 1), a2 + hstep, voffA);
;             PG8_WAIT_V(8); PG8_WAIT_L(0); PG8_BAR; PG8_MMA(0, 0, At, B0); PG8_MMA(0, 1, At, B1); PG8_BAR; PG8_SCHED;
;             PG8_LDA(At, 1, 1); PG8_STAGE(PG8_SB(1, 0), b3, voffB); PG8_STAGE(PG8_SB(1, 1), b3 + hstep, voffB); PG8_STAGE(PG8_SA(1, 0), a3, voffA);
;             PG8_WAIT_V(8); PG8_WAIT_L(0); PG8_BAR; PG8_MMA(1, 0, At, B0); PG8_MMA(1, 1, At, B1); PG8_BAR; PG8_SCHED;
;         }
;         if (wr == 0) PG8_BAR;
	s_add_i32 s29, 0, 0x18000
	s_add_i32 s30, 0, 0x1c000
	v_add_u32_e32 v142, s29, v177
	v_add_u32_e32 v168, s30, v177
	ds_read_b128 v[130:133], v142
	ds_read_b128 v[134:137], v142 offset:1024
	ds_read_b128 v[138:141], v142 offset:2048
	ds_read_b128 v[142:145], v142 offset:3072
	ds_read_b128 v[146:149], v168
	ds_read_b128 v[150:153], v168 offset:1024
	ds_read_b128 v[164:167], v168 offset:2048
	ds_read_b128 v[168:171], v168 offset:3072
	s_add_u32 s54, s72, 0x40000
	s_addc_u32 s55, s73, 0
	s_mov_b32 m0, s45
	ds_read_b128 v[172:175], v181 offset:32768
	ds_read_b128 v[182:185], v181 offset:33792
	ds_read_b128 v[186:189], v181 offset:34816
	ds_read_b128 v[190:193], v181 offset:35840
	ds_read_b128 v[204:207], v181 offset:36864
	ds_read_b128 v[208:211], v181 offset:37888
	ds_read_b128 v[212:215], v181 offset:38912
	ds_read_b128 v[216:219], v181 offset:39936
	global_load_lds_dwordx4 v154, s[54:55]
	s_mov_b32 m0, s46
	s_nop 0
	global_load_lds_dwordx4 v156, s[54:55]
	s_waitcnt vmcnt(8)
	s_waitcnt lgkmcnt(0)
	s_barrier
	v_mfma_f32_16x16x32_bf16 v[126:129], v[130:133], v[172:175], v[126:129]
	v_mfma_f32_16x16x32_bf16 v[122:125], v[138:141], v[172:175], v[122:125]
	v_mfma_f32_16x16x32_bf16 v[110:113], v[130:133], v[186:189], v[110:113]
	v_mfma_f32_16x16x32_bf16 v[106:109], v[138:141], v[186:189], v[106:109]
	v_mfma_f32_16x16x32_bf16 v[94:97], v[130:133], v[204:207], v[94:97]
	v_mfma_f32_16x16x32_bf16 v[90:93], v[138:141], v[204:207], v[90:93]
	v_mfma_f32_16x16x32_bf16 v[78:81], v[130:133], v[212:215], v[78:81]
	v_mfma_f32_16x16x32_bf16 v[74:77], v[138:141], v[212:215], v[74:77]
	v_mfma_f32_16x16x32_bf16 v[126:129], v[134:137], v[182:185], v[126:129]
	v_mfma_f32_16x16x32_bf16 v[122:125], v[142:145], v[182:185], v[122:125]
	v_mfma_f32_16x16x32_bf16 v[110:113], v[134:137], v[190:193], v[110:113]
	v_mfma_f32_16x16x32_bf16 v[106:109], v[142:145], v[190:193], v[106:109]
	v_mfma_f32_16x16x32_bf16 v[94:97], v[134:137], v[208:211], v[94:97]
	v_mfma_f32_16x16x32_bf16 v[90:93], v[142:145], v[208:211], v[90:93]
	v_mfma_f32_16x16x32_bf16 v[78:81], v[134:137], v[216:219], v[78:81]
	v_mfma_f32_16x16x32_bf16 v[74:77], v[142:145], v[216:219], v[74:77]
	v_mfma_f32_16x16x32_bf16 v[118:121], v[146:149], v[172:175], v[118:121]
	v_mfma_f32_16x16x32_bf16 v[114:117], v[164:167], v[172:175], v[114:117]
	v_mfma_f32_16x16x32_bf16 v[102:105], v[146:149], v[186:189], v[102:105]
	v_mfma_f32_16x16x32_bf16 v[98:101], v[164:167], v[186:189], v[98:101]
	v_mfma_f32_16x16x32_bf16 v[86:89], v[146:149], v[204:207], v[86:89]
	v_mfma_f32_16x16x32_bf16 v[82:85], v[164:167], v[204:207], v[82:85]
	v_mfma_f32_16x16x32_bf16 v[70:73], v[146:149], v[212:215], v[70:73]
	v_mfma_f32_16x16x32_bf16 v[66:69], v[164:167], v[212:215], v[66:69]
	v_mfma_f32_16x16x32_bf16 v[118:121], v[150:153], v[182:185], v[118:121]
	v_mfma_f32_16x16x32_bf16 v[114:117], v[168:171], v[182:185], v[114:117]
	v_mfma_f32_16x16x32_bf16 v[102:105], v[150:153], v[190:193], v[102:105]
	v_mfma_f32_16x16x32_bf16 v[98:101], v[168:171], v[190:193], v[98:101]
	v_mfma_f32_16x16x32_bf16 v[86:89], v[150:153], v[208:211], v[86:89]
	v_mfma_f32_16x16x32_bf16 v[82:85], v[168:171], v[208:211], v[82:85]
	v_mfma_f32_16x16x32_bf16 v[70:73], v[150:153], v[216:219], v[70:73]
	v_mfma_f32_16x16x32_bf16 v[66:69], v[168:171], v[216:219], v[66:69]
	s_barrier
	s_add_i32 s29, s29, s15
	s_mov_b32 m0, s29
	ds_read_b128 v[172:175], v181 offset:49152
	ds_read_b128 v[182:185], v181 offset:50176
	ds_read_b128 v[186:189], v181 offset:51200
	ds_read_b128 v[190:193], v181 offset:52224
	ds_read_b128 v[204:207], v181 offset:53248
	ds_read_b128 v[208:211], v181 offset:54272
	ds_read_b128 v[212:215], v181 offset:55296
	ds_read_b128 v[216:219], v181 offset:56320
	global_load_lds_dwordx4 v195, s[20:21]
	s_add_i32 m0, s29, 0x2000
	s_add_i32 s29, s30, s15
	global_load_lds_dwordx4 v201, s[20:21]
	s_add_u32 s20, s20, 0x40080
	s_addc_u32 s21, s21, 0
	s_mov_b32 m0, s29
	s_nop 0
	global_load_lds_dwordx4 v0, s[20:21]
	s_add_i32 m0, s29, 0x2000
	s_nop 0
	global_load_lds_dwordx4 v158, s[20:21]
	s_mov_b32 m0, s12
	s_nop 0
	global_load_lds_dwordx4 v221, s[72:73]
	s_mov_b32 m0, s47
	s_nop 0
	global_load_lds_dwordx4 v223, s[72:73]
	s_waitcnt vmcnt(8)
	s_waitcnt lgkmcnt(0)
	s_barrier
	v_mfma_f32_16x16x32_bf16 v[62:65], v[130:133], v[172:175], v[62:65]
	v_mfma_f32_16x16x32_bf16 v[58:61], v[138:141], v[172:175], v[58:61]
	v_mfma_f32_16x16x32_bf16 v[46:49], v[130:133], v[186:189], v[46:49]
	v_mfma_f32_16x16x32_bf16 v[42:45], v[138:141], v[186:189], v[42:45]
	v_mfma_f32_16x16x32_bf16 v[30:33], v[130:133], v[204:207], v[30:33]
	v_mfma_f32_16x16x32_bf16 v[26:29], v[138:141], v[204:207], v[26:29]
	v_mfma_f32_16x16x32_bf16 v[14:17], v[130:133], v[212:215], v[14:17]
	v_mfma_f32_16x16x32_bf16 v[10:13], v[138:141], v[212:215], v[10:13]
	v_mfma_f32_16x16x32_bf16 v[62:65], v[134:137], v[182:185], v[62:65]
	v_mfma_f32_16x16x32_bf16 v[58:61], v[142:145], v[182:185], v[58:61]
	v_mfma_f32_16x16x32_bf16 v[46:49], v[134:137], v[190:193], v[46:49]
	v_mfma_f32_16x16x32_bf16 v[42:45], v[142:145], v[190:193], v[42:45]
	v_mfma_f32_16x16x32_bf16 v[30:33], v[134:137], v[208:211], v[30:33]
	v_mfma_f32_16x16x32_bf16 v[26:29], v[142:145], v[208:211], v[26:29]
	v_mfma_f32_16x16x32_bf16 v[14:17], v[134:137], v[216:219], v[14:17]
	v_mfma_f32_16x16x32_bf16 v[10:13], v[142:145], v[216:219], v[10:13]
	v_mfma_f32_16x16x32_bf16 v[54:57], v[146:149], v[172:175], v[54:57]
	v_mfma_f32_16x16x32_bf16 v[50:53], v[164:167], v[172:175], v[50:53]
	v_mfma_f32_16x16x32_bf16 v[38:41], v[146:149], v[186:189], v[38:41]
	v_mfma_f32_16x16x32_bf16 v[34:37], v[164:167], v[186:189], v[34:37]
	v_mfma_f32_16x16x32_bf16 v[22:25], v[146:149], v[204:207], v[22:25]
	v_mfma_f32_16x16x32_bf16 v[18:21], v[164:167], v[204:207], v[18:21]
	v_mfma_f32_16x16x32_bf16 v[6:9], v[146:149], v[212:215], v[6:9]
	v_mfma_f32_16x16x32_bf16 v[2:5], v[164:167], v[212:215], v[2:5]
	v_mfma_f32_16x16x32_bf16 v[54:57], v[150:153], v[182:185], v[54:57]
	v_mfma_f32_16x16x32_bf16 v[50:53], v[168:171], v[182:185], v[50:53]
	v_mfma_f32_16x16x32_bf16 v[38:41], v[150:153], v[190:193], v[38:41]
	v_mfma_f32_16x16x32_bf16 v[34:37], v[168:171], v[190:193], v[34:37]
	v_mfma_f32_16x16x32_bf16 v[22:25], v[150:153], v[208:211], v[22:25]
	v_mfma_f32_16x16x32_bf16 v[18:21], v[168:171], v[208:211], v[18:21]
	v_mfma_f32_16x16x32_bf16 v[6:9], v[150:153], v[216:219], v[6:9]
	v_mfma_f32_16x16x32_bf16 v[2:5], v[168:171], v[216:219], v[2:5]
	s_barrier
	s_add_i32 s53, s53, 2
	s_add_u32 s51, s51, 0x100
	s_addc_u32 s52, s52, 0
	s_add_u32 s92, s92, 0x100
	s_addc_u32 s93, s93, 0
	s_cmp_gt_u32 s53, 13
	s_cbranch_scc0 .LBB0_397
	s_and_b64 vcc, exec, s[10:11]
	s_cbranch_vccz .LBB0_400
	s_barrier

; #define PG8_STAGE(bufoff, gbase, voff) do { _Pragma("unroll") for (int _i = 0; _i < 2; ++_i) \
;         __builtin_amdgcn_global_load_lds((const gunsigned*)((const gchar*)(gbase) + (voff)[_i]), (LAS unsigned*)(lds + (bufoff) + ldsw + _i * 8192), 16, 0, 0); } while (0)
; #define PG8_LDA(dst, b, h) do { _Pragma("unroll") for (int m = 0; m < 4; ++m) _Pragma("unroll") for (int k = 0; k < 2; ++k) dst[m][k] = *(const LAS bf16x8*)(lds + PG8_SA(b, h) + aoff + m * 2048 + k * 1024); } while (0)
; #define PG8_LDB(dst, b, h) do { _Pragma("unroll") for (int n = 0; n < 2; ++n) _Pragma("unroll") for (int k = 0; k < 2; ++k) dst[n][k] = *(const LAS bf16x8*)(lds + PG8_SB(b, h) + boff + n * 2048 + k * 1024); } while (0)
; #define PG8_MMA(ai, bj, At, Bt) do { __builtin_amdgcn_s_setprio(1); _Pragma("unroll") for (int m = 0; m < 4; ++m) _Pragma("unroll") for (int n = 0; n < 2; ++n) _Pragma("unroll") for (int k = 0; k < 2; ++k) \
;         acc[ai][bj][m][n] = __builtin_amdgcn_mfma_f32_16x16x32_bf16(Bt[n][k], At[m][k], acc[ai][bj][m][n], 0, 0, 0); __builtin_amdgcn_s_setprio(0); } while (0)
; #define PG8_WAIT_V(n) asm volatile("s_waitcnt vmcnt(" #n ")" ::: "memory")
; #define PG8_WAIT_L(n) asm volatile("s_waitcnt lgkmcnt(" #n ")" ::: "memory")
; #define PG8_BAR __builtin_amdgcn_s_barrier()
; #define PG8_SCHED __builtin_amdgcn_sched_barrier(0)
; template <class Epi, class Sched>
; __device__ __forceinline__ void gemm_phase(LAS unsigned char* lds, const int tid, const Gemm g, const Sched& S, const Epi& E) {
;     ...
;             PG8_LDB(B0, 0, 0); PG8_LDB(B1, 0, 1); PG8_SCHED; PG8_LDA(At, 0, 0); PG8_STAGE(PG8_SA(1, 1), a1 + hstep, voffA);
;             PG8_WAIT_V(8); PG8_WAIT_L(0); PG8_BAR; PG8_MMA(0, 0, At, B0); PG8_MMA(0, 1, At, B1); PG8_BAR; PG8_SCHED;
;             PG8_LDA(At, 0, 1); PG8_STAGE(PG8_SB(0, 0), b2, voffB); PG8_STAGE(PG8_SB(0, 1), b2 + hstep, voffB); PG8_STAGE(PG8_SA(0, 0), a2, voffA);
;             PG8_WAIT_V(8); PG8_WAIT_L(0); PG8_BAR; PG8_MMA(1, 0, At, B0); PG8_MMA(1, 1, At, B1); PG8_BAR; PG8_SCHED;
.LBB0_444:
	s_add_u32 s20, s16, 0xfffe0080
	s_addc_u32 s21, s17, -1
	s_add_i32 s29, 0, 0x10000
	s_cmp_eq_u32 s51, 4
	s_cselect_b32 s73, s1, s21
	s_cselect_b32 s72, s5, s20
	v_add_u32_e32 v122, s29, v242
	s_cselect_b32 s21, s15, s31
	s_cselect_b32 s20, s23, s24
	s_add_i32 s30, 0, 0x14000
	ds_read_b128 v[132:135], v122
	ds_read_b128 v[136:139], v122 offset:1024
	ds_read_b128 v[140:143], v122 offset:2048
	ds_read_b128 v[144:147], v122 offset:3072
	v_add_u32_e32 v122, s30, v242
	ds_read_b128 v[148:151], v122
	ds_read_b128 v[152:155], v122 offset:1024
	ds_read_b128 v[156:159], v122 offset:2048
	ds_read_b128 v[160:163], v122 offset:3072
	s_add_i32 m0, s93, 0xc000
	ds_read_b128 v[164:167], v244
	ds_read_b128 v[168:171], v244 offset:1024
	ds_read_b128 v[172:175], v244 offset:2048
	ds_read_b128 v[176:179], v244 offset:3072
	ds_read_b128 v[180:183], v244 offset:4096
	ds_read_b128 v[184:187], v244 offset:5120
	ds_read_b128 v[188:191], v244 offset:6144
	ds_read_b128 v[192:195], v244 offset:7168
	global_load_lds_dwordx4 v212, s[16:17]
	s_add_i32 m0, s93, 0xe000
	s_nop 0
	global_load_lds_dwordx4 v210, s[16:17]
	s_waitcnt vmcnt(8)
	s_waitcnt lgkmcnt(0)
	s_barrier
	v_mfma_f32_16x16x32_bf16 v[128:131], v[132:135], v[164:167], v[128:131]
	v_mfma_f32_16x16x32_bf16 v[122:125], v[140:143], v[164:167], v[124:127]
	v_mfma_f32_16x16x32_bf16 v[110:113], v[132:135], v[172:175], v[110:113]
	v_mfma_f32_16x16x32_bf16 v[106:109], v[140:143], v[172:175], v[106:109]
	v_mfma_f32_16x16x32_bf16 v[94:97], v[132:135], v[180:183], v[94:97]
	v_mfma_f32_16x16x32_bf16 v[90:93], v[140:143], v[180:183], v[90:93]
	v_mfma_f32_16x16x32_bf16 v[78:81], v[132:135], v[188:191], v[78:81]
	v_mfma_f32_16x16x32_bf16 v[74:77], v[140:143], v[188:191], v[74:77]
	v_mfma_f32_16x16x32_bf16 v[128:131], v[136:139], v[168:171], v[128:131]
	v_mfma_f32_16x16x32_bf16 v[122:125], v[144:147], v[168:171], v[122:125]
	v_mfma_f32_16x16x32_bf16 v[110:113], v[136:139], v[176:179], v[110:113]
	v_mfma_f32_16x16x32_bf16 v[106:109], v[144:147], v[176:179], v[106:109]
	v_mfma_f32_16x16x32_bf16 v[94:97], v[136:139], v[184:187], v[94:97]
	v_mfma_f32_16x16x32_bf16 v[90:93], v[144:147], v[184:187], v[90:93]
	v_mfma_f32_16x16x32_bf16 v[78:81], v[136:139], v[192:195], v[78:81]
	v_mfma_f32_16x16x32_bf16 v[74:77], v[144:147], v[192:195], v[74:77]
	v_mfma_f32_16x16x32_bf16 v[118:121], v[148:151], v[164:167], v[118:121]
	v_mfma_f32_16x16x32_bf16 v[114:117], v[156:159], v[164:167], v[114:117]
	v_mfma_f32_16x16x32_bf16 v[102:105], v[148:151], v[172:175], v[102:105]
	v_mfma_f32_16x16x32_bf16 v[98:101], v[156:159], v[172:175], v[98:101]
	v_mfma_f32_16x16x32_bf16 v[86:89], v[148:151], v[180:183], v[86:89]
	v_mfma_f32_16x16x32_bf16 v[82:85], v[156:159], v[180:183], v[82:85]
	v_mfma_f32_16x16x32_bf16 v[70:73], v[148:151], v[188:191], v[70:73]
	v_mfma_f32_16x16x32_bf16 v[66:69], v[156:159], v[188:191], v[66:69]
	v_mfma_f32_16x16x32_bf16 v[118:121], v[152:155], v[168:171], v[118:121]
	v_mfma_f32_16x16x32_bf16 v[114:117], v[160:163], v[168:171], v[114:117]
	v_mfma_f32_16x16x32_bf16 v[102:105], v[152:155], v[176:179], v[102:105]
	v_mfma_f32_16x16x32_bf16 v[98:101], v[160:163], v[176:179], v[98:101]
	v_mfma_f32_16x16x32_bf16 v[86:89], v[152:155], v[184:187], v[86:89]
	v_mfma_f32_16x16x32_bf16 v[82:85], v[160:163], v[184:187], v[82:85]
	v_mfma_f32_16x16x32_bf16 v[70:73], v[152:155], v[192:195], v[70:73]
	v_mfma_f32_16x16x32_bf16 v[66:69], v[160:163], v[192:195], v[66:69]
	s_barrier
	s_add_i32 s29, s29, s42
	s_mov_b32 m0, s29
	ds_read_b128 v[164:167], v244 offset:16384
	ds_read_b128 v[168:171], v244 offset:17408
	ds_read_b128 v[172:175], v244 offset:18432
	ds_read_b128 v[176:179], v244 offset:19456
	ds_read_b128 v[180:183], v244 offset:20480
	ds_read_b128 v[184:187], v244 offset:21504
	ds_read_b128 v[188:191], v244 offset:22528
	ds_read_b128 v[192:195], v244 offset:23552
	global_load_lds_dwordx4 v0, s[20:21]
	s_add_i32 m0, s29, 0x2000
	s_add_u32 s52, s20, 0x20000
	s_addc_u32 s53, s21, 0
	s_add_i32 s29, s30, s42
	global_load_lds_dwordx4 v208, s[20:21]
	s_mov_b32 m0, s29
	s_nop 0
	global_load_lds_dwordx4 v0, s[52:53]
	s_add_i32 m0, s29, 0x2000
	s_nop 0
	global_load_lds_dwordx4 v208, s[52:53]
	s_mov_b32 m0, s93
	s_nop 0
	global_load_lds_dwordx4 v204, s[72:73]
	s_mov_b32 m0, s44
	s_nop 0
	global_load_lds_dwordx4 v206, s[72:73]
	s_waitcnt vmcnt(8)
	s_waitcnt lgkmcnt(0)
	s_barrier
	v_mfma_f32_16x16x32_bf16 v[62:65], v[132:135], v[164:167], v[62:65]
	v_mfma_f32_16x16x32_bf16 v[58:61], v[140:143], v[164:167], v[58:61]
	v_mfma_f32_16x16x32_bf16 v[46:49], v[132:135], v[172:175], v[46:49]
	v_mfma_f32_16x16x32_bf16 v[42:45], v[140:143], v[172:175], v[42:45]
	v_mfma_f32_16x16x32_bf16 v[30:33], v[132:135], v[180:183], v[30:33]
	v_mfma_f32_16x16x32_bf16 v[26:29], v[140:143], v[180:183], v[26:29]
	v_mfma_f32_16x16x32_bf16 v[14:17], v[132:135], v[188:191], v[14:17]
	v_mfma_f32_16x16x32_bf16 v[10:13], v[140:143], v[188:191], v[10:13]
	v_mfma_f32_16x16x32_bf16 v[62:65], v[136:139], v[168:171], v[62:65]
	v_mfma_f32_16x16x32_bf16 v[58:61], v[144:147], v[168:171], v[58:61]
	v_mfma_f32_16x16x32_bf16 v[46:49], v[136:139], v[176:179], v[46:49]
	v_mfma_f32_16x16x32_bf16 v[42:45], v[144:147], v[176:179], v[42:45]
	v_mfma_f32_16x16x32_bf16 v[30:33], v[136:139], v[184:187], v[30:33]
	v_mfma_f32_16x16x32_bf16 v[26:29], v[144:147], v[184:187], v[26:29]
	v_mfma_f32_16x16x32_bf16 v[14:17], v[136:139], v[192:195], v[14:17]
	v_mfma_f32_16x16x32_bf16 v[10:13], v[144:147], v[192:195], v[10:13]
	v_mfma_f32_16x16x32_bf16 v[54:57], v[148:151], v[164:167], v[54:57]
	v_mfma_f32_16x16x32_bf16 v[50:53], v[156:159], v[164:167], v[50:53]
	v_mfma_f32_16x16x32_bf16 v[38:41], v[148:151], v[172:175], v[38:41]
	v_mfma_f32_16x16x32_bf16 v[34:37], v[156:159], v[172:175], v[34:37]
	v_mfma_f32_16x16x32_bf16 v[22:25], v[148:151], v[180:183], v[22:25]
	v_mfma_f32_16x16x32_bf16 v[18:21], v[156:159], v[180:183], v[18:21]
	v_mfma_f32_16x16x32_bf16 v[6:9], v[148:151], v[188:191], v[6:9]
	v_mfma_f32_16x16x32_bf16 v[2:5], v[156:159], v[188:191], v[2:5]
	v_mfma_f32_16x16x32_bf16 v[54:57], v[152:155], v[168:171], v[54:57]
	v_mfma_f32_16x16x32_bf16 v[50:53], v[160:163], v[168:171], v[50:53]
	v_mfma_f32_16x16x32_bf16 v[38:41], v[152:155], v[176:179], v[38:41]
	v_mfma_f32_16x16x32_bf16 v[34:37], v[160:163], v[176:179], v[34:37]
	v_mfma_f32_16x16x32_bf16 v[22:25], v[152:155], v[184:187], v[22:25]
	v_mfma_f32_16x16x32_bf16 v[18:21], v[160:163], v[184:187], v[18:21]
	v_mfma_f32_16x16x32_bf16 v[6:9], v[152:155], v[192:195], v[6:9]
	v_mfma_f32_16x16x32_bf16 v[2:5], v[160:163], v[192:195], v[2:5]
	s_barrier
; #define PG8_STAGE(bufoff, gbase, voff) do { _Pragma("unroll") for (int _i = 0; _i < 2; ++_i) \
;         __builtin_amdgcn_global_load_lds((const gunsigned*)((const gchar*)(gbase) + (voff)[_i]), (LAS unsigned*)(lds + (bufoff) + ldsw + _i * 8192), 16, 0, 0); } while (0)
; #define PG8_LDA(dst, b, h) do { _Pragma("unroll") for (int m = 0; m < 4; ++m) _Pragma("unroll") for (int k = 0; k < 2; ++k) dst[m][k] = *(const LAS bf16x8*)(lds + PG8_SA(b, h) + aoff + m * 2048 + k * 1024); } while (0)
; #define PG8_LDB(dst, b, h) do { _Pragma("unroll") for (int n = 0; n < 2; ++n) _Pragma("unroll") for (int k = 0; k < 2; ++k) dst[n][k] = *(const LAS bf16x8*)(lds + PG8_SB(b, h) + boff + n * 2048 + k * 1024); } while (0)
; #define PG8_MMA(ai, bj, At, Bt) do { __builtin_amdgcn_s_setprio(1); _Pragma("unroll") for (int m = 0; m < 4; ++m) _Pragma("unroll") for (int n = 0; n < 2; ++n) _Pragma("unroll") for (int k = 0; k < 2; ++k) \
;         acc[ai][bj][m][n] = __builtin_amdgcn_mfma_f32_16x16x32_bf16(Bt[n][k], At[m][k], acc[ai][bj][m][n], 0, 0, 0); __builtin_amdgcn_s_setprio(0); } while (0)
; #define PG8_WAIT_V(n) asm volatile("s_waitcnt vmcnt(" #n ")" ::: "memory")
; #define PG8_WAIT_L(n) asm volatile("s_waitcnt lgkmcnt(" #n ")" ::: "memory")
; #define PG8_BAR __builtin_amdgcn_s_barrier()
; #define PG8_SCHED __builtin_amdgcn_sched_barrier(0)
; template <class Epi, class Sched>
; __device__ __forceinline__ void gemm_phase(LAS unsigned char* lds, const int tid, const Gemm g, const Sched& S, const Epi& E) {
;     ...
;             PG8_LDB(B0, 1, 0); PG8_LDB(B1, 1, 1); PG8_SCHED; PG8_LDA(At, 1, 0); PG8_STAGE(PG8_SA(0, 1), a2 + hstep, voffA);
;             PG8_WAIT_V(8); PG8_WAIT_L(0); PG8_BAR; PG8_MMA(0, 0, At, B0); PG8_MMA(0, 1, At, B1); PG8_BAR; PG8_SCHED;
;             PG8_LDA(At, 1, 1); PG8_STAGE(PG8_SB(1, 0), b3, voffB); PG8_STAGE(PG8_SB(1, 1), b3 + hstep, voffB); PG8_STAGE(PG8_SA(1, 0), a3, voffA);
;             PG8_WAIT_V(8); PG8_WAIT_L(0); PG8_BAR; PG8_MMA(1, 0, At, B0); PG8_MMA(1, 1, At, B1); PG8_BAR; PG8_SCHED;
;         }
;         if (wr == 0) PG8_BAR;
	s_add_i32 s29, 0, 0x18000
	v_add_u32_e32 v126, s29, v242
	s_add_i32 s30, 0, 0x1c000
	ds_read_b128 v[132:135], v126
	ds_read_b128 v[136:139], v126 offset:1024
	ds_read_b128 v[140:143], v126 offset:2048
	ds_read_b128 v[144:147], v126 offset:3072
	v_add_u32_e32 v126, s30, v242
	ds_read_b128 v[148:151], v126
	ds_read_b128 v[152:155], v126 offset:1024
	ds_read_b128 v[156:159], v126 offset:2048
	ds_read_b128 v[160:163], v126 offset:3072
	s_add_u32 s52, s72, 0x20000
	s_addc_u32 s53, s73, 0
	s_mov_b32 m0, s45
	ds_read_b128 v[164:167], v244 offset:32768
	ds_read_b128 v[168:171], v244 offset:33792
	ds_read_b128 v[172:175], v244 offset:34816
	ds_read_b128 v[176:179], v244 offset:35840
	ds_read_b128 v[180:183], v244 offset:36864
	ds_read_b128 v[184:187], v244 offset:37888
	ds_read_b128 v[188:191], v244 offset:38912
	ds_read_b128 v[192:195], v244 offset:39936
	global_load_lds_dwordx4 v204, s[52:53]
	s_mov_b32 m0, s46
	s_nop 0
	global_load_lds_dwordx4 v206, s[52:53]
	s_waitcnt vmcnt(8)
	s_waitcnt lgkmcnt(0)
	s_barrier
	v_mfma_f32_16x16x32_bf16 v[126:129], v[132:135], v[164:167], v[128:131]
	v_mfma_f32_16x16x32_bf16 v[122:125], v[140:143], v[164:167], v[122:125]
	v_mfma_f32_16x16x32_bf16 v[110:113], v[132:135], v[172:175], v[110:113]
	v_mfma_f32_16x16x32_bf16 v[106:109], v[140:143], v[172:175], v[106:109]
	v_mfma_f32_16x16x32_bf16 v[94:97], v[132:135], v[180:183], v[94:97]
	v_mfma_f32_16x16x32_bf16 v[90:93], v[140:143], v[180:183], v[90:93]
	v_mfma_f32_16x16x32_bf16 v[78:81], v[132:135], v[188:191], v[78:81]
	v_mfma_f32_16x16x32_bf16 v[74:77], v[140:143], v[188:191], v[74:77]
	v_mfma_f32_16x16x32_bf16 v[128:131], v[136:139], v[168:171], v[126:129]
	v_mfma_f32_16x16x32_bf16 v[124:127], v[144:147], v[168:171], v[122:125]
	v_mfma_f32_16x16x32_bf16 v[110:113], v[136:139], v[176:179], v[110:113]
	v_mfma_f32_16x16x32_bf16 v[106:109], v[144:147], v[176:179], v[106:109]
	v_mfma_f32_16x16x32_bf16 v[94:97], v[136:139], v[184:187], v[94:97]
	v_mfma_f32_16x16x32_bf16 v[90:93], v[144:147], v[184:187], v[90:93]
	v_mfma_f32_16x16x32_bf16 v[78:81], v[136:139], v[192:195], v[78:81]
	v_mfma_f32_16x16x32_bf16 v[74:77], v[144:147], v[192:195], v[74:77]
	v_mfma_f32_16x16x32_bf16 v[118:121], v[148:151], v[164:167], v[118:121]
	v_mfma_f32_16x16x32_bf16 v[114:117], v[156:159], v[164:167], v[114:117]
	v_mfma_f32_16x16x32_bf16 v[102:105], v[148:151], v[172:175], v[102:105]
	v_mfma_f32_16x16x32_bf16 v[98:101], v[156:159], v[172:175], v[98:101]
	v_mfma_f32_16x16x32_bf16 v[86:89], v[148:151], v[180:183], v[86:89]
	v_mfma_f32_16x16x32_bf16 v[82:85], v[156:159], v[180:183], v[82:85]
	v_mfma_f32_16x16x32_bf16 v[70:73], v[148:151], v[188:191], v[70:73]
	v_mfma_f32_16x16x32_bf16 v[66:69], v[156:159], v[188:191], v[66:69]
	v_mfma_f32_16x16x32_bf16 v[118:121], v[152:155], v[168:171], v[118:121]
	v_mfma_f32_16x16x32_bf16 v[114:117], v[160:163], v[168:171], v[114:117]
	v_mfma_f32_16x16x32_bf16 v[102:105], v[152:155], v[176:179], v[102:105]
	v_mfma_f32_16x16x32_bf16 v[98:101], v[160:163], v[176:179], v[98:101]
	v_mfma_f32_16x16x32_bf16 v[86:89], v[152:155], v[184:187], v[86:89]
	v_mfma_f32_16x16x32_bf16 v[82:85], v[160:163], v[184:187], v[82:85]
	v_mfma_f32_16x16x32_bf16 v[70:73], v[152:155], v[192:195], v[70:73]
	v_mfma_f32_16x16x32_bf16 v[66:69], v[160:163], v[192:195], v[66:69]
	s_barrier
	s_add_i32 s29, s29, s42
	s_mov_b32 m0, s29
	ds_read_b128 v[164:167], v244 offset:49152
	ds_read_b128 v[168:171], v244 offset:50176
	ds_read_b128 v[172:175], v244 offset:51200
	ds_read_b128 v[176:179], v244 offset:52224
	ds_read_b128 v[180:183], v244 offset:53248
	ds_read_b128 v[184:187], v244 offset:54272
	ds_read_b128 v[188:191], v244 offset:55296
	ds_read_b128 v[192:195], v244 offset:56320
	global_load_lds_dwordx4 v201, s[20:21]
	s_add_i32 m0, s29, 0x2000
	s_add_i32 s29, s30, s42
	global_load_lds_dwordx4 v215, s[20:21]
	s_add_u32 s20, s20, 0x20080
	s_addc_u32 s21, s21, 0
	s_mov_b32 m0, s29
	s_nop 0
	global_load_lds_dwordx4 v0, s[20:21]
	s_add_i32 m0, s29, 0x2000
	s_nop 0
	global_load_lds_dwordx4 v208, s[20:21]
	s_mov_b32 m0, s47
	s_nop 0
	global_load_lds_dwordx4 v217, s[72:73]
	s_mov_b32 m0, s48
	s_nop 0
	global_load_lds_dwordx4 v219, s[72:73]
	s_waitcnt vmcnt(8)
	s_waitcnt lgkmcnt(0)
	s_barrier
	v_mfma_f32_16x16x32_bf16 v[62:65], v[132:135], v[164:167], v[62:65]
	v_mfma_f32_16x16x32_bf16 v[58:61], v[140:143], v[164:167], v[58:61]
	v_mfma_f32_16x16x32_bf16 v[46:49], v[132:135], v[172:175], v[46:49]
	v_mfma_f32_16x16x32_bf16 v[42:45], v[140:143], v[172:175], v[42:45]
	v_mfma_f32_16x16x32_bf16 v[30:33], v[132:135], v[180:183], v[30:33]
	v_mfma_f32_16x16x32_bf16 v[26:29], v[140:143], v[180:183], v[26:29]
	v_mfma_f32_16x16x32_bf16 v[14:17], v[132:135], v[188:191], v[14:17]
	v_mfma_f32_16x16x32_bf16 v[10:13], v[140:143], v[188:191], v[10:13]
	v_mfma_f32_16x16x32_bf16 v[62:65], v[136:139], v[168:171], v[62:65]
	v_mfma_f32_16x16x32_bf16 v[58:61], v[144:147], v[168:171], v[58:61]
	v_mfma_f32_16x16x32_bf16 v[46:49], v[136:139], v[176:179], v[46:49]
	v_mfma_f32_16x16x32_bf16 v[42:45], v[144:147], v[176:179], v[42:45]
	v_mfma_f32_16x16x32_bf16 v[30:33], v[136:139], v[184:187], v[30:33]
	v_mfma_f32_16x16x32_bf16 v[26:29], v[144:147], v[184:187], v[26:29]
	v_mfma_f32_16x16x32_bf16 v[14:17], v[136:139], v[192:195], v[14:17]
	v_mfma_f32_16x16x32_bf16 v[10:13], v[144:147], v[192:195], v[10:13]
	v_mfma_f32_16x16x32_bf16 v[54:57], v[148:151], v[164:167], v[54:57]
	v_mfma_f32_16x16x32_bf16 v[50:53], v[156:159], v[164:167], v[50:53]
	v_mfma_f32_16x16x32_bf16 v[38:41], v[148:151], v[172:175], v[38:41]
	v_mfma_f32_16x16x32_bf16 v[34:37], v[156:159], v[172:175], v[34:37]
	v_mfma_f32_16x16x32_bf16 v[22:25], v[148:151], v[180:183], v[22:25]
	v_mfma_f32_16x16x32_bf16 v[18:21], v[156:159], v[180:183], v[18:21]
	v_mfma_f32_16x16x32_bf16 v[6:9], v[148:151], v[188:191], v[6:9]
	v_mfma_f32_16x16x32_bf16 v[2:5], v[156:159], v[188:191], v[2:5]
	v_mfma_f32_16x16x32_bf16 v[54:57], v[152:155], v[168:171], v[54:57]
	v_mfma_f32_16x16x32_bf16 v[50:53], v[160:163], v[168:171], v[50:53]
	v_mfma_f32_16x16x32_bf16 v[38:41], v[152:155], v[176:179], v[38:41]
	v_mfma_f32_16x16x32_bf16 v[34:37], v[160:163], v[176:179], v[34:37]
	v_mfma_f32_16x16x32_bf16 v[22:25], v[152:155], v[184:187], v[22:25]
	v_mfma_f32_16x16x32_bf16 v[18:21], v[160:163], v[184:187], v[18:21]
	v_mfma_f32_16x16x32_bf16 v[6:9], v[152:155], v[192:195], v[6:9]
	v_mfma_f32_16x16x32_bf16 v[2:5], v[160:163], v[192:195], v[2:5]
	s_barrier
	s_add_i32 s51, s51, 2
	s_add_u32 s24, s24, 0x100
	s_addc_u32 s31, s31, 0
	s_add_u32 s16, s16, 0x100
	s_addc_u32 s17, s17, 0
	s_cmp_gt_u32 s51, 5
	s_cbranch_scc0 .LBB0_444
	s_and_b64 vcc, exec, s[10:11]
	s_cbranch_vccz .LBB0_447
	s_barrier

; #define PG8_STAGE(bufoff, gbase, voff) do { _Pragma("unroll") for (int _i = 0; _i < 2; ++_i) \
;         __builtin_amdgcn_global_load_lds((const gunsigned*)((const gchar*)(gbase) + (voff)[_i]), (LAS unsigned*)(lds + (bufoff) + ldsw + _i * 8192), 16, 0, 0); } while (0)
; #define PG8_LDA(dst, b, h) do { _Pragma("unroll") for (int m = 0; m < 4; ++m) _Pragma("unroll") for (int k = 0; k < 2; ++k) dst[m][k] = *(const LAS bf16x8*)(lds + PG8_SA(b, h) + aoff + m * 2048 + k * 1024); } while (0)
; #define PG8_LDB(dst, b, h) do { _Pragma("unroll") for (int n = 0; n < 2; ++n) _Pragma("unroll") for (int k = 0; k < 2; ++k) dst[n][k] = *(const LAS bf16x8*)(lds + PG8_SB(b, h) + boff + n * 2048 + k * 1024); } while (0)
; #define PG8_MMA(ai, bj, At, Bt) do { __builtin_amdgcn_s_setprio(1); _Pragma("unroll") for (int m = 0; m < 4; ++m) _Pragma("unroll") for (int n = 0; n < 2; ++n) _Pragma("unroll") for (int k = 0; k < 2; ++k) \
;         acc[ai][bj][m][n] = __builtin_amdgcn_mfma_f32_16x16x32_bf16(Bt[n][k], At[m][k], acc[ai][bj][m][n], 0, 0, 0); __builtin_amdgcn_s_setprio(0); } while (0)
; #define PG8_WAIT_V(n) asm volatile("s_waitcnt vmcnt(" #n ")" ::: "memory")
; #define PG8_WAIT_L(n) asm volatile("s_waitcnt lgkmcnt(" #n ")" ::: "memory")
; #define PG8_BAR __builtin_amdgcn_s_barrier()
; #define PG8_SCHED __builtin_amdgcn_sched_barrier(0)
; template <class Epi, class Sched>
; __device__ __forceinline__ void gemm_phase(LAS unsigned char* lds, const int tid, const Gemm g, const Sched& S, const Epi& E) {
;     ...
;             PG8_LDB(B0, 0, 0); PG8_LDB(B1, 0, 1); PG8_SCHED; PG8_LDA(At, 0, 0); PG8_STAGE(PG8_SA(1, 1), a1 + hstep, voffA);
;             PG8_WAIT_V(8); PG8_WAIT_L(0); PG8_BAR; PG8_MMA(0, 0, At, B0); PG8_MMA(0, 1, At, B1); PG8_BAR; PG8_SCHED;
;             PG8_LDA(At, 0, 1); PG8_STAGE(PG8_SB(0, 0), b2, voffB); PG8_STAGE(PG8_SB(0, 1), b2 + hstep, voffB); PG8_STAGE(PG8_SA(0, 0), a2, voffA);
;             PG8_WAIT_V(8); PG8_WAIT_L(0); PG8_BAR; PG8_MMA(1, 0, At, B0); PG8_MMA(1, 1, At, B1); PG8_BAR; PG8_SCHED;
.LBB0_559:
	s_add_u32 s20, s60, 0xfffc0080
	s_addc_u32 s21, s61, -1
	s_add_i32 s29, 0, 0x10000
	s_cmp_eq_u32 s46, 12
	s_cselect_b32 s63, s9, s21
	s_cselect_b32 s62, s42, s20
	s_cselect_b32 s21, s7, s45
	s_cselect_b32 s20, s43, s44
	s_add_i32 s30, 0, 0x14000
	v_add_u32_e32 v152, s29, v165
	v_add_u32_e32 v160, s30, v165
	ds_read_b128 v[130:133], v152
	ds_read_b128 v[144:147], v152 offset:1024
	ds_read_b128 v[148:151], v152 offset:2048
	ds_read_b128 v[152:155], v152 offset:3072
	ds_read_b128 v[156:159], v160
	ds_read_b128 v[170:173], v160 offset:1024
	ds_read_b128 v[174:177], v160 offset:2048
	ds_read_b128 v[178:181], v160 offset:3072
	s_add_i32 m0, s34, 0xc000
	ds_read_b128 v[182:185], v169
	ds_read_b128 v[186:189], v169 offset:1024
	ds_read_b128 v[190:193], v169 offset:2048
	ds_read_b128 v[204:207], v169 offset:3072
	ds_read_b128 v[210:213], v169 offset:4096
	ds_read_b128 v[214:217], v169 offset:5120
	ds_read_b128 v[218:221], v169 offset:6144
	ds_read_b128 v[222:225], v169 offset:7168
	global_load_lds_dwordx4 v142, s[60:61]
	s_add_i32 m0, s34, 0xe000
	s_nop 0
	global_load_lds_dwordx4 v140, s[60:61]
	s_waitcnt vmcnt(8)
	s_waitcnt lgkmcnt(0)
	s_barrier
	v_mfma_f32_16x16x32_bf16 v[126:129], v[130:133], v[182:185], v[126:129]
	v_mfma_f32_16x16x32_bf16 v[122:125], v[148:151], v[182:185], v[122:125]
	v_mfma_f32_16x16x32_bf16 v[118:121], v[130:133], v[190:193], v[118:121]
	v_mfma_f32_16x16x32_bf16 v[110:113], v[148:151], v[190:193], v[110:113]
	v_mfma_f32_16x16x32_bf16 v[102:105], v[130:133], v[210:213], v[102:105]
	v_mfma_f32_16x16x32_bf16 v[94:97], v[148:151], v[210:213], v[94:97]
	v_mfma_f32_16x16x32_bf16 v[86:89], v[130:133], v[218:221], v[86:89]
	v_mfma_f32_16x16x32_bf16 v[78:81], v[148:151], v[218:221], v[78:81]
	v_mfma_f32_16x16x32_bf16 v[126:129], v[144:147], v[186:189], v[126:129]
	v_mfma_f32_16x16x32_bf16 v[122:125], v[152:155], v[186:189], v[122:125]
	v_mfma_f32_16x16x32_bf16 v[118:121], v[144:147], v[204:207], v[118:121]
	v_mfma_f32_16x16x32_bf16 v[110:113], v[152:155], v[204:207], v[110:113]
	v_mfma_f32_16x16x32_bf16 v[102:105], v[144:147], v[214:217], v[102:105]
	v_mfma_f32_16x16x32_bf16 v[94:97], v[152:155], v[214:217], v[94:97]
	v_mfma_f32_16x16x32_bf16 v[86:89], v[144:147], v[222:225], v[86:89]
	v_mfma_f32_16x16x32_bf16 v[78:81], v[152:155], v[222:225], v[78:81]
	v_mfma_f32_16x16x32_bf16 v[114:117], v[156:159], v[182:185], v[114:117]
	v_mfma_f32_16x16x32_bf16 v[106:109], v[174:177], v[182:185], v[106:109]
	v_mfma_f32_16x16x32_bf16 v[98:101], v[156:159], v[190:193], v[98:101]
	v_mfma_f32_16x16x32_bf16 v[90:93], v[174:177], v[190:193], v[90:93]
	v_mfma_f32_16x16x32_bf16 v[82:85], v[156:159], v[210:213], v[82:85]
	v_mfma_f32_16x16x32_bf16 v[74:77], v[174:177], v[210:213], v[74:77]
	v_mfma_f32_16x16x32_bf16 v[70:73], v[156:159], v[218:221], v[70:73]
	v_mfma_f32_16x16x32_bf16 v[66:69], v[174:177], v[218:221], v[66:69]
	v_mfma_f32_16x16x32_bf16 v[114:117], v[170:173], v[186:189], v[114:117]
	v_mfma_f32_16x16x32_bf16 v[106:109], v[178:181], v[186:189], v[106:109]
	v_mfma_f32_16x16x32_bf16 v[98:101], v[170:173], v[204:207], v[98:101]
	v_mfma_f32_16x16x32_bf16 v[90:93], v[178:181], v[204:207], v[90:93]
	v_mfma_f32_16x16x32_bf16 v[82:85], v[170:173], v[214:217], v[82:85]
	v_mfma_f32_16x16x32_bf16 v[74:77], v[178:181], v[214:217], v[74:77]
	v_mfma_f32_16x16x32_bf16 v[70:73], v[170:173], v[222:225], v[70:73]
	v_mfma_f32_16x16x32_bf16 v[66:69], v[178:181], v[222:225], v[66:69]
	s_barrier
	s_add_i32 s29, s29, s12
	s_mov_b32 m0, s29
	ds_read_b128 v[182:185], v169 offset:16384
	ds_read_b128 v[186:189], v169 offset:17408
	ds_read_b128 v[190:193], v169 offset:18432
	ds_read_b128 v[204:207], v169 offset:19456
	ds_read_b128 v[210:213], v169 offset:20480
	ds_read_b128 v[214:217], v169 offset:21504
	ds_read_b128 v[218:221], v169 offset:22528
	ds_read_b128 v[222:225], v169 offset:23552
	global_load_lds_dwordx4 v0, s[20:21]
	s_add_i32 m0, s29, 0x2000
	s_add_u32 s48, s20, 0x40000
	s_addc_u32 s49, s21, 0
	s_add_i32 s29, s30, s12
	global_load_lds_dwordx4 v134, s[20:21]
	s_mov_b32 m0, s29
	s_nop 0
	global_load_lds_dwordx4 v0, s[48:49]
	s_add_i32 m0, s29, 0x2000
	s_nop 0
	global_load_lds_dwordx4 v134, s[48:49]
	s_mov_b32 m0, s34
	s_nop 0
	global_load_lds_dwordx4 v138, s[62:63]
	s_mov_b32 m0, s35
	s_nop 0
	global_load_lds_dwordx4 v136, s[62:63]
	s_waitcnt vmcnt(8)
	s_waitcnt lgkmcnt(0)
	s_barrier
	v_mfma_f32_16x16x32_bf16 v[62:65], v[130:133], v[182:185], v[62:65]
	v_mfma_f32_16x16x32_bf16 v[58:61], v[148:151], v[182:185], v[58:61]
	v_mfma_f32_16x16x32_bf16 v[54:57], v[130:133], v[190:193], v[54:57]
	v_mfma_f32_16x16x32_bf16 v[46:49], v[148:151], v[190:193], v[46:49]
	v_mfma_f32_16x16x32_bf16 v[38:41], v[130:133], v[210:213], v[38:41]
	v_mfma_f32_16x16x32_bf16 v[30:33], v[148:151], v[210:213], v[30:33]
	v_mfma_f32_16x16x32_bf16 v[22:25], v[130:133], v[218:221], v[22:25]
	v_mfma_f32_16x16x32_bf16 v[14:17], v[148:151], v[218:221], v[14:17]
	v_mfma_f32_16x16x32_bf16 v[62:65], v[144:147], v[186:189], v[62:65]
	v_mfma_f32_16x16x32_bf16 v[58:61], v[152:155], v[186:189], v[58:61]
	v_mfma_f32_16x16x32_bf16 v[54:57], v[144:147], v[204:207], v[54:57]
	v_mfma_f32_16x16x32_bf16 v[46:49], v[152:155], v[204:207], v[46:49]
	v_mfma_f32_16x16x32_bf16 v[38:41], v[144:147], v[214:217], v[38:41]
	v_mfma_f32_16x16x32_bf16 v[30:33], v[152:155], v[214:217], v[30:33]
	v_mfma_f32_16x16x32_bf16 v[22:25], v[144:147], v[222:225], v[22:25]
	v_mfma_f32_16x16x32_bf16 v[14:17], v[152:155], v[222:225], v[14:17]
	v_mfma_f32_16x16x32_bf16 v[50:53], v[156:159], v[182:185], v[50:53]
	v_mfma_f32_16x16x32_bf16 v[42:45], v[174:177], v[182:185], v[42:45]
	v_mfma_f32_16x16x32_bf16 v[34:37], v[156:159], v[190:193], v[34:37]
	v_mfma_f32_16x16x32_bf16 v[26:29], v[174:177], v[190:193], v[26:29]
	v_mfma_f32_16x16x32_bf16 v[18:21], v[156:159], v[210:213], v[18:21]
	v_mfma_f32_16x16x32_bf16 v[10:13], v[174:177], v[210:213], v[10:13]
	v_mfma_f32_16x16x32_bf16 v[6:9], v[156:159], v[218:221], v[6:9]
	v_mfma_f32_16x16x32_bf16 v[2:5], v[174:177], v[218:221], v[2:5]
	v_mfma_f32_16x16x32_bf16 v[50:53], v[170:173], v[186:189], v[50:53]
	v_mfma_f32_16x16x32_bf16 v[42:45], v[178:181], v[186:189], v[42:45]
	v_mfma_f32_16x16x32_bf16 v[34:37], v[170:173], v[204:207], v[34:37]
	v_mfma_f32_16x16x32_bf16 v[26:29], v[178:181], v[204:207], v[26:29]
	v_mfma_f32_16x16x32_bf16 v[18:21], v[170:173], v[214:217], v[18:21]
	v_mfma_f32_16x16x32_bf16 v[10:13], v[178:181], v[214:217], v[10:13]
	v_mfma_f32_16x16x32_bf16 v[6:9], v[170:173], v[222:225], v[6:9]
	v_mfma_f32_16x16x32_bf16 v[2:5], v[178:181], v[222:225], v[2:5]
	s_barrier
; #define PG8_STAGE(bufoff, gbase, voff) do { _Pragma("unroll") for (int _i = 0; _i < 2; ++_i) \
;         __builtin_amdgcn_global_load_lds((const gunsigned*)((const gchar*)(gbase) + (voff)[_i]), (LAS unsigned*)(lds + (bufoff) + ldsw + _i * 8192), 16, 0, 0); } while (0)
; #define PG8_LDA(dst, b, h) do { _Pragma("unroll") for (int m = 0; m < 4; ++m) _Pragma("unroll") for (int k = 0; k < 2; ++k) dst[m][k] = *(const LAS bf16x8*)(lds + PG8_SA(b, h) + aoff + m * 2048 + k * 1024); } while (0)
; #define PG8_LDB(dst, b, h) do { _Pragma("unroll") for (int n = 0; n < 2; ++n) _Pragma("unroll") for (int k = 0; k < 2; ++k) dst[n][k] = *(const LAS bf16x8*)(lds + PG8_SB(b, h) + boff + n * 2048 + k * 1024); } while (0)
; #define PG8_MMA(ai, bj, At, Bt) do { __builtin_amdgcn_s_setprio(1); _Pragma("unroll") for (int m = 0; m < 4; ++m) _Pragma("unroll") for (int n = 0; n < 2; ++n) _Pragma("unroll") for (int k = 0; k < 2; ++k) \
;         acc[ai][bj][m][n] = __builtin_amdgcn_mfma_f32_16x16x32_bf16(Bt[n][k], At[m][k], acc[ai][bj][m][n], 0, 0, 0); __builtin_amdgcn_s_setprio(0); } while (0)
; #define PG8_WAIT_V(n) asm volatile("s_waitcnt vmcnt(" #n ")" ::: "memory")
; #define PG8_WAIT_L(n) asm volatile("s_waitcnt lgkmcnt(" #n ")" ::: "memory")
; #define PG8_BAR __builtin_amdgcn_s_barrier()
; #define PG8_SCHED __builtin_amdgcn_sched_barrier(0)
; template <class Epi, class Sched>
; __device__ __forceinline__ void gemm_phase(LAS unsigned char* lds, const int tid, const Gemm g, const Sched& S, const Epi& E) {
;     ...
;             PG8_LDB(B0, 1, 0); PG8_LDB(B1, 1, 1); PG8_SCHED; PG8_LDA(At, 1, 0); PG8_STAGE(PG8_SA(0, 1), a2 + hstep, voffA);
;             PG8_WAIT_V(8); PG8_WAIT_L(0); PG8_BAR; PG8_MMA(0, 0, At, B0); PG8_MMA(0, 1, At, B1); PG8_BAR; PG8_SCHED;
;             PG8_LDA(At, 1, 1); PG8_STAGE(PG8_SB(1, 0), b3, voffB); PG8_STAGE(PG8_SB(1, 1), b3 + hstep, voffB); PG8_STAGE(PG8_SA(1, 0), a3, voffA);
;             PG8_WAIT_V(8); PG8_WAIT_L(0); PG8_BAR; PG8_MMA(1, 0, At, B0); PG8_MMA(1, 1, At, B1); PG8_BAR; PG8_SCHED;
;         }
;         if (wr == 0) PG8_BAR;
	s_add_i32 s29, 0, 0x18000
	s_add_i32 s30, 0, 0x1c000
	v_add_u32_e32 v152, s29, v165
	v_add_u32_e32 v162, s30, v165
	ds_read_b128 v[130:133], v152
	ds_read_b128 v[144:147], v152 offset:1024
	ds_read_b128 v[148:151], v152 offset:2048
	ds_read_b128 v[152:155], v152 offset:3072
	ds_read_b128 v[156:159], v162
	ds_read_b128 v[170:173], v162 offset:1024
	ds_read_b128 v[174:177], v162 offset:2048
	ds_read_b128 v[178:181], v162 offset:3072
	s_add_u32 s48, s62, 0x40000
	s_addc_u32 s49, s63, 0
	s_mov_b32 m0, s36
	ds_read_b128 v[182:185], v169 offset:32768
	ds_read_b128 v[186:189], v169 offset:33792
	ds_read_b128 v[190:193], v169 offset:34816
	ds_read_b128 v[204:207], v169 offset:35840
	ds_read_b128 v[210:213], v169 offset:36864
	ds_read_b128 v[214:217], v169 offset:37888
	ds_read_b128 v[218:221], v169 offset:38912
	ds_read_b128 v[222:225], v169 offset:39936
	global_load_lds_dwordx4 v138, s[48:49]
	s_mov_b32 m0, s37
	s_nop 0
	global_load_lds_dwordx4 v136, s[48:49]
	s_waitcnt vmcnt(8)
	s_waitcnt lgkmcnt(0)
	s_barrier
	v_mfma_f32_16x16x32_bf16 v[126:129], v[130:133], v[182:185], v[126:129]
	v_mfma_f32_16x16x32_bf16 v[122:125], v[148:151], v[182:185], v[122:125]
	v_mfma_f32_16x16x32_bf16 v[118:121], v[130:133], v[190:193], v[118:121]
	v_mfma_f32_16x16x32_bf16 v[110:113], v[148:151], v[190:193], v[110:113]
	v_mfma_f32_16x16x32_bf16 v[102:105], v[130:133], v[210:213], v[102:105]
	v_mfma_f32_16x16x32_bf16 v[94:97], v[148:151], v[210:213], v[94:97]
	v_mfma_f32_16x16x32_bf16 v[86:89], v[130:133], v[218:221], v[86:89]
	v_mfma_f32_16x16x32_bf16 v[78:81], v[148:151], v[218:221], v[78:81]
	v_mfma_f32_16x16x32_bf16 v[126:129], v[144:147], v[186:189], v[126:129]
	v_mfma_f32_16x16x32_bf16 v[122:125], v[152:155], v[186:189], v[122:125]
	v_mfma_f32_16x16x32_bf16 v[118:121], v[144:147], v[204:207], v[118:121]
	v_mfma_f32_16x16x32_bf16 v[110:113], v[152:155], v[204:207], v[110:113]
	v_mfma_f32_16x16x32_bf16 v[102:105], v[144:147], v[214:217], v[102:105]
	v_mfma_f32_16x16x32_bf16 v[94:97], v[152:155], v[214:217], v[94:97]
	v_mfma_f32_16x16x32_bf16 v[86:89], v[144:147], v[222:225], v[86:89]
	v_mfma_f32_16x16x32_bf16 v[78:81], v[152:155], v[222:225], v[78:81]
	v_mfma_f32_16x16x32_bf16 v[114:117], v[156:159], v[182:185], v[114:117]
	v_mfma_f32_16x16x32_bf16 v[106:109], v[174:177], v[182:185], v[106:109]
	v_mfma_f32_16x16x32_bf16 v[98:101], v[156:159], v[190:193], v[98:101]
	v_mfma_f32_16x16x32_bf16 v[90:93], v[174:177], v[190:193], v[90:93]
	v_mfma_f32_16x16x32_bf16 v[82:85], v[156:159], v[210:213], v[82:85]
	v_mfma_f32_16x16x32_bf16 v[74:77], v[174:177], v[210:213], v[74:77]
	v_mfma_f32_16x16x32_bf16 v[70:73], v[156:159], v[218:221], v[70:73]
	v_mfma_f32_16x16x32_bf16 v[66:69], v[174:177], v[218:221], v[66:69]
	v_mfma_f32_16x16x32_bf16 v[114:117], v[170:173], v[186:189], v[114:117]
	v_mfma_f32_16x16x32_bf16 v[106:109], v[178:181], v[186:189], v[106:109]
	v_mfma_f32_16x16x32_bf16 v[98:101], v[170:173], v[204:207], v[98:101]
	v_mfma_f32_16x16x32_bf16 v[90:93], v[178:181], v[204:207], v[90:93]
	v_mfma_f32_16x16x32_bf16 v[82:85], v[170:173], v[214:217], v[82:85]
	v_mfma_f32_16x16x32_bf16 v[74:77], v[178:181], v[214:217], v[74:77]
	v_mfma_f32_16x16x32_bf16 v[70:73], v[170:173], v[222:225], v[70:73]
	v_mfma_f32_16x16x32_bf16 v[66:69], v[178:181], v[222:225], v[66:69]
	s_barrier
	s_add_i32 s29, s29, s12
	s_mov_b32 m0, s29
	ds_read_b128 v[182:185], v169 offset:49152
	ds_read_b128 v[186:189], v169 offset:50176
	ds_read_b128 v[190:193], v169 offset:51200
	ds_read_b128 v[204:207], v169 offset:52224
	ds_read_b128 v[210:213], v169 offset:53248
	ds_read_b128 v[214:217], v169 offset:54272
	ds_read_b128 v[218:221], v169 offset:55296
	ds_read_b128 v[222:225], v169 offset:56320
	global_load_lds_dwordx4 v161, s[20:21]
	s_add_i32 m0, s29, 0x2000
	s_add_i32 s29, s30, s12
	global_load_lds_dwordx4 v195, s[20:21]
	s_add_u32 s20, s20, 0x40080
	s_addc_u32 s21, s21, 0
	s_mov_b32 m0, s29
	s_nop 0
	global_load_lds_dwordx4 v0, s[20:21]
	s_add_i32 m0, s29, 0x2000
	s_nop 0
	global_load_lds_dwordx4 v134, s[20:21]
	s_mov_b32 m0, s38
	s_nop 0
	global_load_lds_dwordx4 v201, s[62:63]
	s_mov_b32 m0, s39
	s_nop 0
	global_load_lds_dwordx4 v227, s[62:63]
	s_waitcnt vmcnt(8)
	s_waitcnt lgkmcnt(0)
	s_barrier
	v_mfma_f32_16x16x32_bf16 v[62:65], v[130:133], v[182:185], v[62:65]
	v_mfma_f32_16x16x32_bf16 v[58:61], v[148:151], v[182:185], v[58:61]
	v_mfma_f32_16x16x32_bf16 v[54:57], v[130:133], v[190:193], v[54:57]
	v_mfma_f32_16x16x32_bf16 v[46:49], v[148:151], v[190:193], v[46:49]
	v_mfma_f32_16x16x32_bf16 v[38:41], v[130:133], v[210:213], v[38:41]
	v_mfma_f32_16x16x32_bf16 v[30:33], v[148:151], v[210:213], v[30:33]
	v_mfma_f32_16x16x32_bf16 v[22:25], v[130:133], v[218:221], v[22:25]
	v_mfma_f32_16x16x32_bf16 v[14:17], v[148:151], v[218:221], v[14:17]
	v_mfma_f32_16x16x32_bf16 v[62:65], v[144:147], v[186:189], v[62:65]
	v_mfma_f32_16x16x32_bf16 v[58:61], v[152:155], v[186:189], v[58:61]
	v_mfma_f32_16x16x32_bf16 v[54:57], v[144:147], v[204:207], v[54:57]
	v_mfma_f32_16x16x32_bf16 v[46:49], v[152:155], v[204:207], v[46:49]
	v_mfma_f32_16x16x32_bf16 v[38:41], v[144:147], v[214:217], v[38:41]
	v_mfma_f32_16x16x32_bf16 v[30:33], v[152:155], v[214:217], v[30:33]
	v_mfma_f32_16x16x32_bf16 v[22:25], v[144:147], v[222:225], v[22:25]
	v_mfma_f32_16x16x32_bf16 v[14:17], v[152:155], v[222:225], v[14:17]
	v_mfma_f32_16x16x32_bf16 v[50:53], v[156:159], v[182:185], v[50:53]
	v_mfma_f32_16x16x32_bf16 v[42:45], v[174:177], v[182:185], v[42:45]
	v_mfma_f32_16x16x32_bf16 v[34:37], v[156:159], v[190:193], v[34:37]
	v_mfma_f32_16x16x32_bf16 v[26:29], v[174:177], v[190:193], v[26:29]
	v_mfma_f32_16x16x32_bf16 v[18:21], v[156:159], v[210:213], v[18:21]
	v_mfma_f32_16x16x32_bf16 v[10:13], v[174:177], v[210:213], v[10:13]
	v_mfma_f32_16x16x32_bf16 v[6:9], v[156:159], v[218:221], v[6:9]
	v_mfma_f32_16x16x32_bf16 v[2:5], v[174:177], v[218:221], v[2:5]
	v_mfma_f32_16x16x32_bf16 v[50:53], v[170:173], v[186:189], v[50:53]
	v_mfma_f32_16x16x32_bf16 v[42:45], v[178:181], v[186:189], v[42:45]
	v_mfma_f32_16x16x32_bf16 v[34:37], v[170:173], v[204:207], v[34:37]
	v_mfma_f32_16x16x32_bf16 v[26:29], v[178:181], v[204:207], v[26:29]
	v_mfma_f32_16x16x32_bf16 v[18:21], v[170:173], v[214:217], v[18:21]
	v_mfma_f32_16x16x32_bf16 v[10:13], v[178:181], v[214:217], v[10:13]
	v_mfma_f32_16x16x32_bf16 v[6:9], v[170:173], v[222:225], v[6:9]
	v_mfma_f32_16x16x32_bf16 v[2:5], v[178:181], v[222:225], v[2:5]
	s_barrier
	s_add_i32 s46, s46, 2
	s_add_u32 s44, s44, 0x100
	s_addc_u32 s45, s45, 0
	s_add_u32 s60, s60, 0x100
	s_addc_u32 s61, s61, 0
	s_cmp_gt_u32 s46, 13
	s_cbranch_scc0 .LBB0_559
	s_and_b64 vcc, exec, s[4:5]
	s_cbranch_vccz .LBB0_562
	s_barrier

; #define PG8_STAGE(bufoff, gbase, voff) do { _Pragma("unroll") for (int _i = 0; _i < 2; ++_i) \
;         __builtin_amdgcn_global_load_lds((const gunsigned*)((const gchar*)(gbase) + (voff)[_i]), (LAS unsigned*)(lds + (bufoff) + ldsw + _i * 8192), 16, 0, 0); } while (0)
; #define PG8_LDA(dst, b, h) do { _Pragma("unroll") for (int m = 0; m < 4; ++m) _Pragma("unroll") for (int k = 0; k < 2; ++k) dst[m][k] = *(const LAS bf16x8*)(lds + PG8_SA(b, h) + aoff + m * 2048 + k * 1024); } while (0)
; #define PG8_LDB(dst, b, h) do { _Pragma("unroll") for (int n = 0; n < 2; ++n) _Pragma("unroll") for (int k = 0; k < 2; ++k) dst[n][k] = *(const LAS bf16x8*)(lds + PG8_SB(b, h) + boff + n * 2048 + k * 1024); } while (0)
; #define PG8_MMA(ai, bj, At, Bt) do { __builtin_amdgcn_s_setprio(1); _Pragma("unroll") for (int m = 0; m < 4; ++m) _Pragma("unroll") for (int n = 0; n < 2; ++n) _Pragma("unroll") for (int k = 0; k < 2; ++k) \
;         acc[ai][bj][m][n] = __builtin_amdgcn_mfma_f32_16x16x32_bf16(Bt[n][k], At[m][k], acc[ai][bj][m][n], 0, 0, 0); __builtin_amdgcn_s_setprio(0); } while (0)
; #define PG8_WAIT_V(n) asm volatile("s_waitcnt vmcnt(" #n ")" ::: "memory")
; #define PG8_WAIT_L(n) asm volatile("s_waitcnt lgkmcnt(" #n ")" ::: "memory")
; #define PG8_BAR __builtin_amdgcn_s_barrier()
; #define PG8_SCHED __builtin_amdgcn_sched_barrier(0)
; template <class Epi, class Sched>
; __device__ __forceinline__ void gemm_phase(LAS unsigned char* lds, const int tid, const Gemm g, const Sched& S, const Epi& E) {
;     ...
;             PG8_LDB(B0, 0, 0); PG8_LDB(B1, 0, 1); PG8_SCHED; PG8_LDA(At, 0, 0); PG8_STAGE(PG8_SA(1, 1), a1 + hstep, voffA);
;             PG8_WAIT_V(8); PG8_WAIT_L(0); PG8_BAR; PG8_MMA(0, 0, At, B0); PG8_MMA(0, 1, At, B1); PG8_BAR; PG8_SCHED;
;             PG8_LDA(At, 0, 1); PG8_STAGE(PG8_SB(0, 0), b2, voffB); PG8_STAGE(PG8_SB(0, 1), b2 + hstep, voffB); PG8_STAGE(PG8_SA(0, 0), a2, voffA);
;             PG8_WAIT_V(8); PG8_WAIT_L(0); PG8_BAR; PG8_MMA(1, 0, At, B0); PG8_MMA(1, 1, At, B1); PG8_BAR; PG8_SCHED;
.LBB0_598:
	s_add_u32 s20, s62, 0x100
	s_addc_u32 s21, s63, 0
	s_add_i32 s29, 0, 0x10000
	s_cmp_eq_u32 s45, 40
	s_cselect_b32 s73, s9, s21
	s_cselect_b32 s72, s8, s20
	s_cselect_b32 s67, s61, s44
	s_cselect_b32 s66, s60, s31
	s_add_i32 s48, 0, 0x14000
	v_add_u32_e32 v142, s29, v210
	v_add_u32_e32 v158, s48, v210
	ds_read_b128 v[130:133], v142
	ds_read_b128 v[134:137], v142 offset:1024
	ds_read_b128 v[138:141], v142 offset:2048
	ds_read_b128 v[142:145], v142 offset:3072
	ds_read_b128 v[146:149], v158
	ds_read_b128 v[150:153], v158 offset:1024
	ds_read_b128 v[154:157], v158 offset:2048
	ds_read_b128 v[158:161], v158 offset:3072
	s_add_i32 m0, s34, 0xc000
	ds_read_b128 v[162:165], v214
	ds_read_b128 v[166:169], v214 offset:1024
	ds_read_b128 v[170:173], v214 offset:2048
	ds_read_b128 v[174:177], v214 offset:3072
	ds_read_b128 v[188:191], v214 offset:4096
	ds_read_b128 v[192:195], v214 offset:5120
	ds_read_b128 v[204:207], v214 offset:6144
	ds_read_b128 v[216:219], v214 offset:7168
	global_load_lds_dwordx4 v186, s[62:63]
	s_add_i32 m0, s34, 0xe000
	s_nop 0
	global_load_lds_dwordx4 v184, s[62:63]
	s_waitcnt vmcnt(8)
	s_waitcnt lgkmcnt(0)
	s_barrier
	v_mfma_f32_16x16x32_bf16 v[126:129], v[130:133], v[162:165], v[126:129]
	v_mfma_f32_16x16x32_bf16 v[122:125], v[138:141], v[162:165], v[122:125]
	v_mfma_f32_16x16x32_bf16 v[110:113], v[130:133], v[170:173], v[110:113]
	v_mfma_f32_16x16x32_bf16 v[106:109], v[138:141], v[170:173], v[106:109]
	v_mfma_f32_16x16x32_bf16 v[94:97], v[130:133], v[188:191], v[94:97]
	v_mfma_f32_16x16x32_bf16 v[90:93], v[138:141], v[188:191], v[90:93]
	v_mfma_f32_16x16x32_bf16 v[78:81], v[130:133], v[204:207], v[78:81]
	v_mfma_f32_16x16x32_bf16 v[74:77], v[138:141], v[204:207], v[74:77]
	v_mfma_f32_16x16x32_bf16 v[126:129], v[134:137], v[166:169], v[126:129]
	v_mfma_f32_16x16x32_bf16 v[122:125], v[142:145], v[166:169], v[122:125]
	v_mfma_f32_16x16x32_bf16 v[110:113], v[134:137], v[174:177], v[110:113]
	v_mfma_f32_16x16x32_bf16 v[106:109], v[142:145], v[174:177], v[106:109]
	v_mfma_f32_16x16x32_bf16 v[94:97], v[134:137], v[192:195], v[94:97]
	v_mfma_f32_16x16x32_bf16 v[90:93], v[142:145], v[192:195], v[90:93]
	v_mfma_f32_16x16x32_bf16 v[78:81], v[134:137], v[216:219], v[78:81]
	v_mfma_f32_16x16x32_bf16 v[74:77], v[142:145], v[216:219], v[74:77]
	v_mfma_f32_16x16x32_bf16 v[118:121], v[146:149], v[162:165], v[118:121]
	v_mfma_f32_16x16x32_bf16 v[114:117], v[154:157], v[162:165], v[114:117]
	v_mfma_f32_16x16x32_bf16 v[102:105], v[146:149], v[170:173], v[102:105]
	v_mfma_f32_16x16x32_bf16 v[98:101], v[154:157], v[170:173], v[98:101]
	v_mfma_f32_16x16x32_bf16 v[86:89], v[146:149], v[188:191], v[86:89]
	v_mfma_f32_16x16x32_bf16 v[82:85], v[154:157], v[188:191], v[82:85]
	v_mfma_f32_16x16x32_bf16 v[70:73], v[146:149], v[204:207], v[70:73]
	v_mfma_f32_16x16x32_bf16 v[66:69], v[154:157], v[204:207], v[66:69]
	v_mfma_f32_16x16x32_bf16 v[118:121], v[150:153], v[166:169], v[118:121]
	v_mfma_f32_16x16x32_bf16 v[114:117], v[158:161], v[166:169], v[114:117]
	v_mfma_f32_16x16x32_bf16 v[102:105], v[150:153], v[174:177], v[102:105]
	v_mfma_f32_16x16x32_bf16 v[98:101], v[158:161], v[174:177], v[98:101]
	v_mfma_f32_16x16x32_bf16 v[86:89], v[150:153], v[192:195], v[86:89]
	v_mfma_f32_16x16x32_bf16 v[82:85], v[158:161], v[192:195], v[82:85]
	v_mfma_f32_16x16x32_bf16 v[70:73], v[150:153], v[216:219], v[70:73]
	v_mfma_f32_16x16x32_bf16 v[66:69], v[158:161], v[216:219], v[66:69]
	s_barrier
	s_add_i32 s29, s29, s15
	s_mov_b32 m0, s29
	ds_read_b128 v[162:165], v214 offset:16384
	ds_read_b128 v[166:169], v214 offset:17408
	ds_read_b128 v[170:173], v214 offset:18432
	ds_read_b128 v[174:177], v214 offset:19456
	ds_read_b128 v[188:191], v214 offset:20480
	ds_read_b128 v[192:195], v214 offset:21504
	ds_read_b128 v[204:207], v214 offset:22528
	ds_read_b128 v[216:219], v214 offset:23552
	global_load_lds_dwordx4 v0, s[66:67]
	s_add_i32 m0, s29, 0x2000
	s_add_u32 s46, s66, 0xb0000
	s_addc_u32 s47, s67, 0
	s_add_i32 s29, s48, s15
	global_load_lds_dwordx4 v182, s[66:67]
	s_mov_b32 m0, s29
	s_nop 0
	global_load_lds_dwordx4 v0, s[46:47]
	s_add_i32 m0, s29, 0x2000
	s_nop 0
	global_load_lds_dwordx4 v182, s[46:47]
	s_mov_b32 m0, s34
	s_nop 0
	global_load_lds_dwordx4 v178, s[72:73]
	s_mov_b32 m0, s12
	s_nop 0
	global_load_lds_dwordx4 v180, s[72:73]
	s_waitcnt vmcnt(8)
	s_waitcnt lgkmcnt(0)
	s_barrier
	v_mfma_f32_16x16x32_bf16 v[62:65], v[130:133], v[162:165], v[62:65]
	v_mfma_f32_16x16x32_bf16 v[58:61], v[138:141], v[162:165], v[58:61]
	v_mfma_f32_16x16x32_bf16 v[46:49], v[130:133], v[170:173], v[46:49]
	v_mfma_f32_16x16x32_bf16 v[42:45], v[138:141], v[170:173], v[42:45]
	v_mfma_f32_16x16x32_bf16 v[30:33], v[130:133], v[188:191], v[30:33]
	v_mfma_f32_16x16x32_bf16 v[26:29], v[138:141], v[188:191], v[26:29]
	v_mfma_f32_16x16x32_bf16 v[14:17], v[130:133], v[204:207], v[14:17]
	v_mfma_f32_16x16x32_bf16 v[10:13], v[138:141], v[204:207], v[10:13]
	v_mfma_f32_16x16x32_bf16 v[62:65], v[134:137], v[166:169], v[62:65]
	v_mfma_f32_16x16x32_bf16 v[58:61], v[142:145], v[166:169], v[58:61]
	v_mfma_f32_16x16x32_bf16 v[46:49], v[134:137], v[174:177], v[46:49]
	v_mfma_f32_16x16x32_bf16 v[42:45], v[142:145], v[174:177], v[42:45]
	v_mfma_f32_16x16x32_bf16 v[30:33], v[134:137], v[192:195], v[30:33]
	v_mfma_f32_16x16x32_bf16 v[26:29], v[142:145], v[192:195], v[26:29]
	v_mfma_f32_16x16x32_bf16 v[14:17], v[134:137], v[216:219], v[14:17]
	v_mfma_f32_16x16x32_bf16 v[10:13], v[142:145], v[216:219], v[10:13]
	v_mfma_f32_16x16x32_bf16 v[54:57], v[146:149], v[162:165], v[54:57]
	v_mfma_f32_16x16x32_bf16 v[50:53], v[154:157], v[162:165], v[50:53]
	v_mfma_f32_16x16x32_bf16 v[38:41], v[146:149], v[170:173], v[38:41]
	v_mfma_f32_16x16x32_bf16 v[34:37], v[154:157], v[170:173], v[34:37]
	v_mfma_f32_16x16x32_bf16 v[22:25], v[146:149], v[188:191], v[22:25]
	v_mfma_f32_16x16x32_bf16 v[18:21], v[154:157], v[188:191], v[18:21]
	v_mfma_f32_16x16x32_bf16 v[6:9], v[146:149], v[204:207], v[6:9]
	v_mfma_f32_16x16x32_bf16 v[2:5], v[154:157], v[204:207], v[2:5]
	v_mfma_f32_16x16x32_bf16 v[54:57], v[150:153], v[166:169], v[54:57]
	v_mfma_f32_16x16x32_bf16 v[50:53], v[158:161], v[166:169], v[50:53]
	v_mfma_f32_16x16x32_bf16 v[38:41], v[150:153], v[174:177], v[38:41]
	v_mfma_f32_16x16x32_bf16 v[34:37], v[158:161], v[174:177], v[34:37]
	v_mfma_f32_16x16x32_bf16 v[22:25], v[150:153], v[192:195], v[22:25]
	v_mfma_f32_16x16x32_bf16 v[18:21], v[158:161], v[192:195], v[18:21]
	v_mfma_f32_16x16x32_bf16 v[6:9], v[150:153], v[216:219], v[6:9]
	v_mfma_f32_16x16x32_bf16 v[2:5], v[158:161], v[216:219], v[2:5]
	s_barrier
; #define PG8_STAGE(bufoff, gbase, voff) do { _Pragma("unroll") for (int _i = 0; _i < 2; ++_i) \
;         __builtin_amdgcn_global_load_lds((const gunsigned*)((const gchar*)(gbase) + (voff)[_i]), (LAS unsigned*)(lds + (bufoff) + ldsw + _i * 8192), 16, 0, 0); } while (0)
; #define PG8_LDA(dst, b, h) do { _Pragma("unroll") for (int m = 0; m < 4; ++m) _Pragma("unroll") for (int k = 0; k < 2; ++k) dst[m][k] = *(const LAS bf16x8*)(lds + PG8_SA(b, h) + aoff + m * 2048 + k * 1024); } while (0)
; #define PG8_LDB(dst, b, h) do { _Pragma("unroll") for (int n = 0; n < 2; ++n) _Pragma("unroll") for (int k = 0; k < 2; ++k) dst[n][k] = *(const LAS bf16x8*)(lds + PG8_SB(b, h) + boff + n * 2048 + k * 1024); } while (0)
; #define PG8_MMA(ai, bj, At, Bt) do { __builtin_amdgcn_s_setprio(1); _Pragma("unroll") for (int m = 0; m < 4; ++m) _Pragma("unroll") for (int n = 0; n < 2; ++n) _Pragma("unroll") for (int k = 0; k < 2; ++k) \
;         acc[ai][bj][m][n] = __builtin_amdgcn_mfma_f32_16x16x32_bf16(Bt[n][k], At[m][k], acc[ai][bj][m][n], 0, 0, 0); __builtin_amdgcn_s_setprio(0); } while (0)
; #define PG8_WAIT_V(n) asm volatile("s_waitcnt vmcnt(" #n ")" ::: "memory")
; #define PG8_WAIT_L(n) asm volatile("s_waitcnt lgkmcnt(" #n ")" ::: "memory")
; #define PG8_BAR __builtin_amdgcn_s_barrier()
; #define PG8_SCHED __builtin_amdgcn_sched_barrier(0)
; template <class Epi, class Sched>
; __device__ __forceinline__ void gemm_phase(LAS unsigned char* lds, const int tid, const Gemm g, const Sched& S, const Epi& E) {
;     ...
;             PG8_LDB(B0, 1, 0); PG8_LDB(B1, 1, 1); PG8_SCHED; PG8_LDA(At, 1, 0); PG8_STAGE(PG8_SA(0, 1), a2 + hstep, voffA);
;             PG8_WAIT_V(8); PG8_WAIT_L(0); PG8_BAR; PG8_MMA(0, 0, At, B0); PG8_MMA(0, 1, At, B1); PG8_BAR; PG8_SCHED;
;             PG8_LDA(At, 1, 1); PG8_STAGE(PG8_SB(1, 0), b3, voffB); PG8_STAGE(PG8_SB(1, 1), b3 + hstep, voffB); PG8_STAGE(PG8_SA(1, 0), a3, voffA);
;             PG8_WAIT_V(8); PG8_WAIT_L(0); PG8_BAR; PG8_MMA(1, 0, At, B0); PG8_MMA(1, 1, At, B1); PG8_BAR; PG8_SCHED;
;         }
;         if (wr == 0) PG8_BAR;
	s_add_i32 s29, 0, 0x18000
	s_add_i32 s48, 0, 0x1c000
	v_add_u32_e32 v142, s29, v210
	v_add_u32_e32 v158, s48, v210
	ds_read_b128 v[130:133], v142
	ds_read_b128 v[134:137], v142 offset:1024
	ds_read_b128 v[138:141], v142 offset:2048
	ds_read_b128 v[142:145], v142 offset:3072
	ds_read_b128 v[146:149], v158
	ds_read_b128 v[150:153], v158 offset:1024
	ds_read_b128 v[154:157], v158 offset:2048
	ds_read_b128 v[158:161], v158 offset:3072
	s_add_u32 s46, s72, 0xb0000
	s_addc_u32 s47, s73, 0
	s_mov_b32 m0, s35
	ds_read_b128 v[162:165], v214 offset:32768
	ds_read_b128 v[166:169], v214 offset:33792
	ds_read_b128 v[170:173], v214 offset:34816
	ds_read_b128 v[174:177], v214 offset:35840
	ds_read_b128 v[188:191], v214 offset:36864
	ds_read_b128 v[192:195], v214 offset:37888
	ds_read_b128 v[204:207], v214 offset:38912
	ds_read_b128 v[216:219], v214 offset:39936
	global_load_lds_dwordx4 v178, s[46:47]
	s_mov_b32 m0, s36
	s_nop 0
	global_load_lds_dwordx4 v180, s[46:47]
	s_waitcnt vmcnt(8)
	s_waitcnt lgkmcnt(0)
	s_barrier
	v_mfma_f32_16x16x32_bf16 v[126:129], v[130:133], v[162:165], v[126:129]
	v_mfma_f32_16x16x32_bf16 v[122:125], v[138:141], v[162:165], v[122:125]
	v_mfma_f32_16x16x32_bf16 v[110:113], v[130:133], v[170:173], v[110:113]
	v_mfma_f32_16x16x32_bf16 v[106:109], v[138:141], v[170:173], v[106:109]
	v_mfma_f32_16x16x32_bf16 v[94:97], v[130:133], v[188:191], v[94:97]
	v_mfma_f32_16x16x32_bf16 v[90:93], v[138:141], v[188:191], v[90:93]
	v_mfma_f32_16x16x32_bf16 v[78:81], v[130:133], v[204:207], v[78:81]
	v_mfma_f32_16x16x32_bf16 v[74:77], v[138:141], v[204:207], v[74:77]
	v_mfma_f32_16x16x32_bf16 v[126:129], v[134:137], v[166:169], v[126:129]
	v_mfma_f32_16x16x32_bf16 v[122:125], v[142:145], v[166:169], v[122:125]
	v_mfma_f32_16x16x32_bf16 v[110:113], v[134:137], v[174:177], v[110:113]
	v_mfma_f32_16x16x32_bf16 v[106:109], v[142:145], v[174:177], v[106:109]
	v_mfma_f32_16x16x32_bf16 v[94:97], v[134:137], v[192:195], v[94:97]
	v_mfma_f32_16x16x32_bf16 v[90:93], v[142:145], v[192:195], v[90:93]
	v_mfma_f32_16x16x32_bf16 v[78:81], v[134:137], v[216:219], v[78:81]
	v_mfma_f32_16x16x32_bf16 v[74:77], v[142:145], v[216:219], v[74:77]
	v_mfma_f32_16x16x32_bf16 v[118:121], v[146:149], v[162:165], v[118:121]
	v_mfma_f32_16x16x32_bf16 v[114:117], v[154:157], v[162:165], v[114:117]
	v_mfma_f32_16x16x32_bf16 v[102:105], v[146:149], v[170:173], v[102:105]
	v_mfma_f32_16x16x32_bf16 v[98:101], v[154:157], v[170:173], v[98:101]
	v_mfma_f32_16x16x32_bf16 v[86:89], v[146:149], v[188:191], v[86:89]
	v_mfma_f32_16x16x32_bf16 v[82:85], v[154:157], v[188:191], v[82:85]
	v_mfma_f32_16x16x32_bf16 v[70:73], v[146:149], v[204:207], v[70:73]
	v_mfma_f32_16x16x32_bf16 v[66:69], v[154:157], v[204:207], v[66:69]
	v_mfma_f32_16x16x32_bf16 v[118:121], v[150:153], v[166:169], v[118:121]
	v_mfma_f32_16x16x32_bf16 v[114:117], v[158:161], v[166:169], v[114:117]
	v_mfma_f32_16x16x32_bf16 v[102:105], v[150:153], v[174:177], v[102:105]
	v_mfma_f32_16x16x32_bf16 v[98:101], v[158:161], v[174:177], v[98:101]
	v_mfma_f32_16x16x32_bf16 v[86:89], v[150:153], v[192:195], v[86:89]
	v_mfma_f32_16x16x32_bf16 v[82:85], v[158:161], v[192:195], v[82:85]
	v_mfma_f32_16x16x32_bf16 v[70:73], v[150:153], v[216:219], v[70:73]
	v_mfma_f32_16x16x32_bf16 v[66:69], v[158:161], v[216:219], v[66:69]
	s_barrier
	s_add_i32 s29, s29, s15
	s_mov_b32 m0, s29
	ds_read_b128 v[162:165], v214 offset:49152
	ds_read_b128 v[166:169], v214 offset:50176
	ds_read_b128 v[170:173], v214 offset:51200
	ds_read_b128 v[174:177], v214 offset:52224
	ds_read_b128 v[188:191], v214 offset:53248
	ds_read_b128 v[192:195], v214 offset:54272
	ds_read_b128 v[204:207], v214 offset:55296
	ds_read_b128 v[216:219], v214 offset:56320
	global_load_lds_dwordx4 v221, s[66:67]
	s_add_i32 m0, s29, 0x2000
	s_add_u32 s46, s66, 0xb0080
	s_addc_u32 s47, s67, 0
	s_add_i32 s29, s48, s15
	global_load_lds_dwordx4 v223, s[66:67]
	s_mov_b32 m0, s29
	s_nop 0
	global_load_lds_dwordx4 v0, s[46:47]
	s_add_i32 m0, s29, 0x2000
	s_nop 0
	global_load_lds_dwordx4 v182, s[46:47]
	s_mov_b32 m0, s37
	s_nop 0
	global_load_lds_dwordx4 v225, s[72:73]
	s_mov_b32 m0, s38
	s_nop 0
	global_load_lds_dwordx4 v227, s[72:73]
	s_waitcnt vmcnt(8)
	s_waitcnt lgkmcnt(0)
	s_barrier
	v_mfma_f32_16x16x32_bf16 v[62:65], v[130:133], v[162:165], v[62:65]
	v_mfma_f32_16x16x32_bf16 v[58:61], v[138:141], v[162:165], v[58:61]
	v_mfma_f32_16x16x32_bf16 v[46:49], v[130:133], v[170:173], v[46:49]
	v_mfma_f32_16x16x32_bf16 v[42:45], v[138:141], v[170:173], v[42:45]
	v_mfma_f32_16x16x32_bf16 v[30:33], v[130:133], v[188:191], v[30:33]
	v_mfma_f32_16x16x32_bf16 v[26:29], v[138:141], v[188:191], v[26:29]
	v_mfma_f32_16x16x32_bf16 v[14:17], v[130:133], v[204:207], v[14:17]
	v_mfma_f32_16x16x32_bf16 v[10:13], v[138:141], v[204:207], v[10:13]
	v_mfma_f32_16x16x32_bf16 v[62:65], v[134:137], v[166:169], v[62:65]
	v_mfma_f32_16x16x32_bf16 v[58:61], v[142:145], v[166:169], v[58:61]
	v_mfma_f32_16x16x32_bf16 v[46:49], v[134:137], v[174:177], v[46:49]
	v_mfma_f32_16x16x32_bf16 v[42:45], v[142:145], v[174:177], v[42:45]
	v_mfma_f32_16x16x32_bf16 v[30:33], v[134:137], v[192:195], v[30:33]
	v_mfma_f32_16x16x32_bf16 v[26:29], v[142:145], v[192:195], v[26:29]
	v_mfma_f32_16x16x32_bf16 v[14:17], v[134:137], v[216:219], v[14:17]
	v_mfma_f32_16x16x32_bf16 v[10:13], v[142:145], v[216:219], v[10:13]
	v_mfma_f32_16x16x32_bf16 v[54:57], v[146:149], v[162:165], v[54:57]
	v_mfma_f32_16x16x32_bf16 v[50:53], v[154:157], v[162:165], v[50:53]
	v_mfma_f32_16x16x32_bf16 v[38:41], v[146:149], v[170:173], v[38:41]
	v_mfma_f32_16x16x32_bf16 v[34:37], v[154:157], v[170:173], v[34:37]
	v_mfma_f32_16x16x32_bf16 v[22:25], v[146:149], v[188:191], v[22:25]
	v_mfma_f32_16x16x32_bf16 v[18:21], v[154:157], v[188:191], v[18:21]
	v_mfma_f32_16x16x32_bf16 v[6:9], v[146:149], v[204:207], v[6:9]
	v_mfma_f32_16x16x32_bf16 v[2:5], v[154:157], v[204:207], v[2:5]
	v_mfma_f32_16x16x32_bf16 v[54:57], v[150:153], v[166:169], v[54:57]
	v_mfma_f32_16x16x32_bf16 v[50:53], v[158:161], v[166:169], v[50:53]
	v_mfma_f32_16x16x32_bf16 v[38:41], v[150:153], v[174:177], v[38:41]
	v_mfma_f32_16x16x32_bf16 v[34:37], v[158:161], v[174:177], v[34:37]
	v_mfma_f32_16x16x32_bf16 v[22:25], v[150:153], v[192:195], v[22:25]
	v_mfma_f32_16x16x32_bf16 v[18:21], v[158:161], v[192:195], v[18:21]
	v_mfma_f32_16x16x32_bf16 v[6:9], v[150:153], v[216:219], v[6:9]
	v_mfma_f32_16x16x32_bf16 v[2:5], v[158:161], v[216:219], v[2:5]
	s_barrier
	s_add_i32 s45, s45, 2
	s_add_u32 s31, s31, 0x100
	s_addc_u32 s44, s44, 0
	s_cmp_gt_u32 s45, 41
	s_mov_b64 s[62:63], s[20:21]
	s_cbranch_scc0 .LBB0_598
	s_and_b64 vcc, exec, s[58:59]
	s_cbranch_vccz .LBB0_601
	s_barrier

; #define PG8_STAGE(bufoff, gbase, voff) do { _Pragma("unroll") for (int _i = 0; _i < 2; ++_i) \
;         __builtin_amdgcn_global_load_lds((const gunsigned*)((const gchar*)(gbase) + (voff)[_i]), (LAS unsigned*)(lds + (bufoff) + ldsw + _i * 8192), 16, 0, 0); } while (0)
; #define PG8_LDA(dst, b, h) do { _Pragma("unroll") for (int m = 0; m < 4; ++m) _Pragma("unroll") for (int k = 0; k < 2; ++k) dst[m][k] = *(const LAS bf16x8*)(lds + PG8_SA(b, h) + aoff + m * 2048 + k * 1024); } while (0)
; #define PG8_LDB(dst, b, h) do { _Pragma("unroll") for (int n = 0; n < 2; ++n) _Pragma("unroll") for (int k = 0; k < 2; ++k) dst[n][k] = *(const LAS bf16x8*)(lds + PG8_SB(b, h) + boff + n * 2048 + k * 1024); } while (0)
; #define PG8_MMA(ai, bj, At, Bt) do { __builtin_amdgcn_s_setprio(1); _Pragma("unroll") for (int m = 0; m < 4; ++m) _Pragma("unroll") for (int n = 0; n < 2; ++n) _Pragma("unroll") for (int k = 0; k < 2; ++k) \
;         acc[ai][bj][m][n] = __builtin_amdgcn_mfma_f32_16x16x32_bf16(Bt[n][k], At[m][k], acc[ai][bj][m][n], 0, 0, 0); __builtin_amdgcn_s_setprio(0); } while (0)
; #define PG8_WAIT_V(n) asm volatile("s_waitcnt vmcnt(" #n ")" ::: "memory")
; #define PG8_WAIT_L(n) asm volatile("s_waitcnt lgkmcnt(" #n ")" ::: "memory")
; #define PG8_BAR __builtin_amdgcn_s_barrier()
; #define PG8_SCHED __builtin_amdgcn_sched_barrier(0)
; template <class Epi, class Sched>
; __device__ __forceinline__ void gemm_phase(LAS unsigned char* lds, const int tid, const Gemm g, const Sched& S, const Epi& E) {
;     ...
;             PG8_LDB(B0, 0, 0); PG8_LDB(B1, 0, 1); PG8_SCHED; PG8_LDA(At, 0, 0); PG8_STAGE(PG8_SA(1, 1), a1 + hstep, voffA);
;             PG8_WAIT_V(8); PG8_WAIT_L(0); PG8_BAR; PG8_MMA(0, 0, At, B0); PG8_MMA(0, 1, At, B1); PG8_BAR; PG8_SCHED;
;             PG8_LDA(At, 0, 1); PG8_STAGE(PG8_SB(0, 0), b2, voffB); PG8_STAGE(PG8_SB(0, 1), b2 + hstep, voffB); PG8_STAGE(PG8_SA(0, 0), a2, voffA);
;             PG8_WAIT_V(8); PG8_WAIT_L(0); PG8_BAR; PG8_MMA(1, 0, At, B0); PG8_MMA(1, 1, At, B1); PG8_BAR; PG8_SCHED;
.LBB0_647:
	s_add_u32 s20, s58, 0xfffc0080
	s_addc_u32 s21, s59, -1
	s_add_i32 s42, 0, 0x10000
	s_cmp_eq_u32 s41, 12
	s_cselect_b32 s61, s9, s21
	s_cselect_b32 s60, s37, s20
	v_add_u32_e32 v140, s42, v143
	s_cselect_b32 s21, s7, s40
	s_cselect_b32 s20, s38, s39
	s_add_i32 s44, 0, 0x14000
	ds_read_b128 v[146:149], v140
	ds_read_b128 v[150:153], v140 offset:1024
	ds_read_b128 v[154:157], v140 offset:2048
	ds_read_b128 v[158:161], v140 offset:3072
	v_add_u32_e32 v140, s44, v143
	ds_read_b128 v[162:165], v140
	ds_read_b128 v[166:169], v140 offset:1024
	ds_read_b128 v[170:173], v140 offset:2048
	ds_read_b128 v[174:177], v140 offset:3072
	s_add_i32 m0, s23, 0xc000
	ds_read_b128 v[178:181], v145
	ds_read_b128 v[182:185], v145 offset:1024
	ds_read_b128 v[186:189], v145 offset:2048
	ds_read_b128 v[190:193], v145 offset:3072
	ds_read_b128 v[204:207], v145 offset:4096
	ds_read_b128 v[208:211], v145 offset:5120
	ds_read_b128 v[212:215], v145 offset:6144
	ds_read_b128 v[216:219], v145 offset:7168
	global_load_lds_dwordx4 v138, s[58:59]
	s_add_i32 m0, s23, 0xe000
	s_nop 0
	global_load_lds_dwordx4 v136, s[58:59]
	s_waitcnt vmcnt(8)
	s_waitcnt lgkmcnt(0)
	s_barrier
	v_mfma_f32_16x16x32_bf16 v[126:129], v[146:149], v[178:181], v[126:129]
	v_mfma_f32_16x16x32_bf16 v[122:125], v[154:157], v[178:181], v[122:125]
	v_mfma_f32_16x16x32_bf16 v[110:113], v[146:149], v[186:189], v[110:113]
	v_mfma_f32_16x16x32_bf16 v[106:109], v[154:157], v[186:189], v[106:109]
	v_mfma_f32_16x16x32_bf16 v[94:97], v[146:149], v[204:207], v[94:97]
	v_mfma_f32_16x16x32_bf16 v[90:93], v[154:157], v[204:207], v[90:93]
	v_mfma_f32_16x16x32_bf16 v[78:81], v[146:149], v[212:215], v[78:81]
	v_mfma_f32_16x16x32_bf16 v[74:77], v[154:157], v[212:215], v[74:77]
	v_mfma_f32_16x16x32_bf16 v[126:129], v[150:153], v[182:185], v[126:129]
	v_mfma_f32_16x16x32_bf16 v[122:125], v[158:161], v[182:185], v[122:125]
	v_mfma_f32_16x16x32_bf16 v[110:113], v[150:153], v[190:193], v[110:113]
	v_mfma_f32_16x16x32_bf16 v[106:109], v[158:161], v[190:193], v[106:109]
	v_mfma_f32_16x16x32_bf16 v[94:97], v[150:153], v[208:211], v[94:97]
	v_mfma_f32_16x16x32_bf16 v[90:93], v[158:161], v[208:211], v[90:93]
	v_mfma_f32_16x16x32_bf16 v[78:81], v[150:153], v[216:219], v[78:81]
	v_mfma_f32_16x16x32_bf16 v[74:77], v[158:161], v[216:219], v[74:77]
	v_mfma_f32_16x16x32_bf16 v[118:121], v[162:165], v[178:181], v[118:121]
	v_mfma_f32_16x16x32_bf16 v[114:117], v[170:173], v[178:181], v[114:117]
	v_mfma_f32_16x16x32_bf16 v[102:105], v[162:165], v[186:189], v[102:105]
	v_mfma_f32_16x16x32_bf16 v[98:101], v[170:173], v[186:189], v[98:101]
	v_mfma_f32_16x16x32_bf16 v[86:89], v[162:165], v[204:207], v[86:89]
	v_mfma_f32_16x16x32_bf16 v[82:85], v[170:173], v[204:207], v[82:85]
	v_mfma_f32_16x16x32_bf16 v[70:73], v[162:165], v[212:215], v[70:73]
	v_mfma_f32_16x16x32_bf16 v[66:69], v[170:173], v[212:215], v[66:69]
	v_mfma_f32_16x16x32_bf16 v[118:121], v[166:169], v[182:185], v[118:121]
	v_mfma_f32_16x16x32_bf16 v[114:117], v[174:177], v[182:185], v[114:117]
	v_mfma_f32_16x16x32_bf16 v[102:105], v[166:169], v[190:193], v[102:105]
	v_mfma_f32_16x16x32_bf16 v[98:101], v[174:177], v[190:193], v[98:101]
	v_mfma_f32_16x16x32_bf16 v[86:89], v[166:169], v[208:211], v[86:89]
	v_mfma_f32_16x16x32_bf16 v[82:85], v[174:177], v[208:211], v[82:85]
	v_mfma_f32_16x16x32_bf16 v[70:73], v[166:169], v[216:219], v[70:73]
	v_mfma_f32_16x16x32_bf16 v[66:69], v[174:177], v[216:219], v[66:69]
	s_barrier
	s_add_i32 s42, s42, s12
	s_mov_b32 m0, s42
	ds_read_b128 v[178:181], v145 offset:16384
	ds_read_b128 v[182:185], v145 offset:17408
	ds_read_b128 v[186:189], v145 offset:18432
	ds_read_b128 v[190:193], v145 offset:19456
	ds_read_b128 v[204:207], v145 offset:20480
	ds_read_b128 v[208:211], v145 offset:21504
	ds_read_b128 v[212:215], v145 offset:22528
	ds_read_b128 v[216:219], v145 offset:23552
	global_load_lds_dwordx4 v0, s[20:21]
	s_add_i32 m0, s42, 0x2000
	s_add_u32 s42, s20, 0x40000
	s_addc_u32 s43, s21, 0
	s_add_i32 s44, s44, s12
	global_load_lds_dwordx4 v130, s[20:21]
	s_mov_b32 m0, s44
	s_nop 0
	global_load_lds_dwordx4 v0, s[42:43]
	s_add_i32 m0, s44, 0x2000
	s_nop 0
	global_load_lds_dwordx4 v130, s[42:43]
	s_mov_b32 m0, s23
	s_nop 0
	global_load_lds_dwordx4 v134, s[60:61]
	s_mov_b32 m0, s24
	s_nop 0
	global_load_lds_dwordx4 v132, s[60:61]
	s_waitcnt vmcnt(8)
	s_waitcnt lgkmcnt(0)
	s_barrier
	v_mfma_f32_16x16x32_bf16 v[62:65], v[146:149], v[178:181], v[62:65]
	v_mfma_f32_16x16x32_bf16 v[58:61], v[154:157], v[178:181], v[58:61]
	v_mfma_f32_16x16x32_bf16 v[46:49], v[146:149], v[186:189], v[46:49]
	v_mfma_f32_16x16x32_bf16 v[42:45], v[154:157], v[186:189], v[42:45]
	v_mfma_f32_16x16x32_bf16 v[30:33], v[146:149], v[204:207], v[30:33]
	v_mfma_f32_16x16x32_bf16 v[26:29], v[154:157], v[204:207], v[26:29]
	v_mfma_f32_16x16x32_bf16 v[14:17], v[146:149], v[212:215], v[14:17]
	v_mfma_f32_16x16x32_bf16 v[10:13], v[154:157], v[212:215], v[10:13]
	v_mfma_f32_16x16x32_bf16 v[62:65], v[150:153], v[182:185], v[62:65]
	v_mfma_f32_16x16x32_bf16 v[58:61], v[158:161], v[182:185], v[58:61]
	v_mfma_f32_16x16x32_bf16 v[46:49], v[150:153], v[190:193], v[46:49]
	v_mfma_f32_16x16x32_bf16 v[42:45], v[158:161], v[190:193], v[42:45]
	v_mfma_f32_16x16x32_bf16 v[30:33], v[150:153], v[208:211], v[30:33]
	v_mfma_f32_16x16x32_bf16 v[26:29], v[158:161], v[208:211], v[26:29]
	v_mfma_f32_16x16x32_bf16 v[14:17], v[150:153], v[216:219], v[14:17]
	v_mfma_f32_16x16x32_bf16 v[10:13], v[158:161], v[216:219], v[10:13]
	v_mfma_f32_16x16x32_bf16 v[54:57], v[162:165], v[178:181], v[54:57]
	v_mfma_f32_16x16x32_bf16 v[50:53], v[170:173], v[178:181], v[50:53]
	v_mfma_f32_16x16x32_bf16 v[38:41], v[162:165], v[186:189], v[38:41]
	v_mfma_f32_16x16x32_bf16 v[34:37], v[170:173], v[186:189], v[34:37]
	v_mfma_f32_16x16x32_bf16 v[22:25], v[162:165], v[204:207], v[22:25]
	v_mfma_f32_16x16x32_bf16 v[18:21], v[170:173], v[204:207], v[18:21]
	v_mfma_f32_16x16x32_bf16 v[6:9], v[162:165], v[212:215], v[6:9]
	v_mfma_f32_16x16x32_bf16 v[2:5], v[170:173], v[212:215], v[2:5]
	v_mfma_f32_16x16x32_bf16 v[54:57], v[166:169], v[182:185], v[54:57]
	v_mfma_f32_16x16x32_bf16 v[50:53], v[174:177], v[182:185], v[50:53]
	v_mfma_f32_16x16x32_bf16 v[38:41], v[166:169], v[190:193], v[38:41]
	v_mfma_f32_16x16x32_bf16 v[34:37], v[174:177], v[190:193], v[34:37]
	v_mfma_f32_16x16x32_bf16 v[22:25], v[166:169], v[208:211], v[22:25]
	v_mfma_f32_16x16x32_bf16 v[18:21], v[174:177], v[208:211], v[18:21]
	v_mfma_f32_16x16x32_bf16 v[6:9], v[166:169], v[216:219], v[6:9]
	v_mfma_f32_16x16x32_bf16 v[2:5], v[174:177], v[216:219], v[2:5]
	s_barrier
; #define PG8_STAGE(bufoff, gbase, voff) do { _Pragma("unroll") for (int _i = 0; _i < 2; ++_i) \
;         __builtin_amdgcn_global_load_lds((const gunsigned*)((const gchar*)(gbase) + (voff)[_i]), (LAS unsigned*)(lds + (bufoff) + ldsw + _i * 8192), 16, 0, 0); } while (0)
; #define PG8_LDA(dst, b, h) do { _Pragma("unroll") for (int m = 0; m < 4; ++m) _Pragma("unroll") for (int k = 0; k < 2; ++k) dst[m][k] = *(const LAS bf16x8*)(lds + PG8_SA(b, h) + aoff + m * 2048 + k * 1024); } while (0)
; #define PG8_LDB(dst, b, h) do { _Pragma("unroll") for (int n = 0; n < 2; ++n) _Pragma("unroll") for (int k = 0; k < 2; ++k) dst[n][k] = *(const LAS bf16x8*)(lds + PG8_SB(b, h) + boff + n * 2048 + k * 1024); } while (0)
; #define PG8_MMA(ai, bj, At, Bt) do { __builtin_amdgcn_s_setprio(1); _Pragma("unroll") for (int m = 0; m < 4; ++m) _Pragma("unroll") for (int n = 0; n < 2; ++n) _Pragma("unroll") for (int k = 0; k < 2; ++k) \
;         acc[ai][bj][m][n] = __builtin_amdgcn_mfma_f32_16x16x32_bf16(Bt[n][k], At[m][k], acc[ai][bj][m][n], 0, 0, 0); __builtin_amdgcn_s_setprio(0); } while (0)
; #define PG8_WAIT_V(n) asm volatile("s_waitcnt vmcnt(" #n ")" ::: "memory")
; #define PG8_WAIT_L(n) asm volatile("s_waitcnt lgkmcnt(" #n ")" ::: "memory")
; #define PG8_BAR __builtin_amdgcn_s_barrier()
; #define PG8_SCHED __builtin_amdgcn_sched_barrier(0)
; template <class Epi, class Sched>
; __device__ __forceinline__ void gemm_phase(LAS unsigned char* lds, const int tid, const Gemm g, const Sched& S, const Epi& E) {
;     ...
;             PG8_LDB(B0, 1, 0); PG8_LDB(B1, 1, 1); PG8_SCHED; PG8_LDA(At, 1, 0); PG8_STAGE(PG8_SA(0, 1), a2 + hstep, voffA);
;             PG8_WAIT_V(8); PG8_WAIT_L(0); PG8_BAR; PG8_MMA(0, 0, At, B0); PG8_MMA(0, 1, At, B1); PG8_BAR; PG8_SCHED;
;             PG8_LDA(At, 1, 1); PG8_STAGE(PG8_SB(1, 0), b3, voffB); PG8_STAGE(PG8_SB(1, 1), b3 + hstep, voffB); PG8_STAGE(PG8_SA(1, 0), a3, voffA);
;             PG8_WAIT_V(8); PG8_WAIT_L(0); PG8_BAR; PG8_MMA(1, 0, At, B0); PG8_MMA(1, 1, At, B1); PG8_BAR; PG8_SCHED;
;         }
;         if (wr == 0) PG8_BAR;
	s_add_i32 s44, 0, 0x18000
	s_add_i32 s45, 0, 0x1c000
	v_add_u32_e32 v158, s44, v143
	v_add_u32_e32 v174, s45, v143
	ds_read_b128 v[146:149], v158
	ds_read_b128 v[150:153], v158 offset:1024
	ds_read_b128 v[154:157], v158 offset:2048
	ds_read_b128 v[158:161], v158 offset:3072
	ds_read_b128 v[162:165], v174
	ds_read_b128 v[166:169], v174 offset:1024
	ds_read_b128 v[170:173], v174 offset:2048
	ds_read_b128 v[174:177], v174 offset:3072
	s_add_u32 s42, s60, 0x40000
	s_addc_u32 s43, s61, 0
	s_mov_b32 m0, s29
	ds_read_b128 v[178:181], v145 offset:32768
	ds_read_b128 v[182:185], v145 offset:33792
	ds_read_b128 v[186:189], v145 offset:34816
	ds_read_b128 v[190:193], v145 offset:35840
	ds_read_b128 v[204:207], v145 offset:36864
	ds_read_b128 v[208:211], v145 offset:37888
	ds_read_b128 v[212:215], v145 offset:38912
	ds_read_b128 v[216:219], v145 offset:39936
	global_load_lds_dwordx4 v134, s[42:43]
	s_mov_b32 m0, s30
	s_nop 0
	global_load_lds_dwordx4 v132, s[42:43]
	s_waitcnt vmcnt(8)
	s_waitcnt lgkmcnt(0)
	s_barrier
	v_mfma_f32_16x16x32_bf16 v[126:129], v[146:149], v[178:181], v[126:129]
	v_mfma_f32_16x16x32_bf16 v[122:125], v[154:157], v[178:181], v[122:125]
	v_mfma_f32_16x16x32_bf16 v[110:113], v[146:149], v[186:189], v[110:113]
	v_mfma_f32_16x16x32_bf16 v[106:109], v[154:157], v[186:189], v[106:109]
	v_mfma_f32_16x16x32_bf16 v[94:97], v[146:149], v[204:207], v[94:97]
	v_mfma_f32_16x16x32_bf16 v[90:93], v[154:157], v[204:207], v[90:93]
	v_mfma_f32_16x16x32_bf16 v[78:81], v[146:149], v[212:215], v[78:81]
	v_mfma_f32_16x16x32_bf16 v[74:77], v[154:157], v[212:215], v[74:77]
	v_mfma_f32_16x16x32_bf16 v[126:129], v[150:153], v[182:185], v[126:129]
	v_mfma_f32_16x16x32_bf16 v[122:125], v[158:161], v[182:185], v[122:125]
	v_mfma_f32_16x16x32_bf16 v[110:113], v[150:153], v[190:193], v[110:113]
	v_mfma_f32_16x16x32_bf16 v[106:109], v[158:161], v[190:193], v[106:109]
	v_mfma_f32_16x16x32_bf16 v[94:97], v[150:153], v[208:211], v[94:97]
	v_mfma_f32_16x16x32_bf16 v[90:93], v[158:161], v[208:211], v[90:93]
	v_mfma_f32_16x16x32_bf16 v[78:81], v[150:153], v[216:219], v[78:81]
	v_mfma_f32_16x16x32_bf16 v[74:77], v[158:161], v[216:219], v[74:77]
	v_mfma_f32_16x16x32_bf16 v[118:121], v[162:165], v[178:181], v[118:121]
	v_mfma_f32_16x16x32_bf16 v[114:117], v[170:173], v[178:181], v[114:117]
	v_mfma_f32_16x16x32_bf16 v[102:105], v[162:165], v[186:189], v[102:105]
	v_mfma_f32_16x16x32_bf16 v[98:101], v[170:173], v[186:189], v[98:101]
	v_mfma_f32_16x16x32_bf16 v[86:89], v[162:165], v[204:207], v[86:89]
	v_mfma_f32_16x16x32_bf16 v[82:85], v[170:173], v[204:207], v[82:85]
	v_mfma_f32_16x16x32_bf16 v[70:73], v[162:165], v[212:215], v[70:73]
	v_mfma_f32_16x16x32_bf16 v[66:69], v[170:173], v[212:215], v[66:69]
	v_mfma_f32_16x16x32_bf16 v[118:121], v[166:169], v[182:185], v[118:121]
	v_mfma_f32_16x16x32_bf16 v[114:117], v[174:177], v[182:185], v[114:117]
	v_mfma_f32_16x16x32_bf16 v[102:105], v[166:169], v[190:193], v[102:105]
	v_mfma_f32_16x16x32_bf16 v[98:101], v[174:177], v[190:193], v[98:101]
	v_mfma_f32_16x16x32_bf16 v[86:89], v[166:169], v[208:211], v[86:89]
	v_mfma_f32_16x16x32_bf16 v[82:85], v[174:177], v[208:211], v[82:85]
	v_mfma_f32_16x16x32_bf16 v[70:73], v[166:169], v[216:219], v[70:73]
	v_mfma_f32_16x16x32_bf16 v[66:69], v[174:177], v[216:219], v[66:69]
	s_barrier
	s_add_i32 s42, s44, s12
	s_mov_b32 m0, s42
	ds_read_b128 v[178:181], v145 offset:49152
	ds_read_b128 v[182:185], v145 offset:50176
	ds_read_b128 v[186:189], v145 offset:51200
	ds_read_b128 v[190:193], v145 offset:52224
	ds_read_b128 v[204:207], v145 offset:53248
	ds_read_b128 v[208:211], v145 offset:54272
	ds_read_b128 v[212:215], v145 offset:55296
	ds_read_b128 v[216:219], v145 offset:56320
	global_load_lds_dwordx4 v141, s[20:21]
	s_add_i32 m0, s42, 0x2000
	s_add_i32 s42, s45, s12
	global_load_lds_dwordx4 v195, s[20:21]
	s_add_u32 s20, s20, 0x40080
	s_addc_u32 s21, s21, 0
	s_mov_b32 m0, s42
	s_nop 0
	global_load_lds_dwordx4 v0, s[20:21]
	s_add_i32 m0, s42, 0x2000
	s_nop 0
	global_load_lds_dwordx4 v130, s[20:21]
	s_mov_b32 m0, s31
	s_nop 0
	global_load_lds_dwordx4 v221, s[60:61]
	s_mov_b32 m0, s34
	s_nop 0
	global_load_lds_dwordx4 v223, s[60:61]
	s_waitcnt vmcnt(8)
	s_waitcnt lgkmcnt(0)
	s_barrier
	v_mfma_f32_16x16x32_bf16 v[62:65], v[146:149], v[178:181], v[62:65]
	v_mfma_f32_16x16x32_bf16 v[58:61], v[154:157], v[178:181], v[58:61]
	v_mfma_f32_16x16x32_bf16 v[46:49], v[146:149], v[186:189], v[46:49]
	v_mfma_f32_16x16x32_bf16 v[42:45], v[154:157], v[186:189], v[42:45]
	v_mfma_f32_16x16x32_bf16 v[30:33], v[146:149], v[204:207], v[30:33]
	v_mfma_f32_16x16x32_bf16 v[26:29], v[154:157], v[204:207], v[26:29]
	v_mfma_f32_16x16x32_bf16 v[14:17], v[146:149], v[212:215], v[14:17]
	v_mfma_f32_16x16x32_bf16 v[10:13], v[154:157], v[212:215], v[10:13]
	v_mfma_f32_16x16x32_bf16 v[62:65], v[150:153], v[182:185], v[62:65]
	v_mfma_f32_16x16x32_bf16 v[58:61], v[158:161], v[182:185], v[58:61]
	v_mfma_f32_16x16x32_bf16 v[46:49], v[150:153], v[190:193], v[46:49]
	v_mfma_f32_16x16x32_bf16 v[42:45], v[158:161], v[190:193], v[42:45]
	v_mfma_f32_16x16x32_bf16 v[30:33], v[150:153], v[208:211], v[30:33]
	v_mfma_f32_16x16x32_bf16 v[26:29], v[158:161], v[208:211], v[26:29]
	v_mfma_f32_16x16x32_bf16 v[14:17], v[150:153], v[216:219], v[14:17]
	v_mfma_f32_16x16x32_bf16 v[10:13], v[158:161], v[216:219], v[10:13]
	v_mfma_f32_16x16x32_bf16 v[54:57], v[162:165], v[178:181], v[54:57]
	v_mfma_f32_16x16x32_bf16 v[50:53], v[170:173], v[178:181], v[50:53]
	v_mfma_f32_16x16x32_bf16 v[38:41], v[162:165], v[186:189], v[38:41]
	v_mfma_f32_16x16x32_bf16 v[34:37], v[170:173], v[186:189], v[34:37]
	v_mfma_f32_16x16x32_bf16 v[22:25], v[162:165], v[204:207], v[22:25]
	v_mfma_f32_16x16x32_bf16 v[18:21], v[170:173], v[204:207], v[18:21]
	v_mfma_f32_16x16x32_bf16 v[6:9], v[162:165], v[212:215], v[6:9]
	v_mfma_f32_16x16x32_bf16 v[2:5], v[170:173], v[212:215], v[2:5]
	v_mfma_f32_16x16x32_bf16 v[54:57], v[166:169], v[182:185], v[54:57]
	v_mfma_f32_16x16x32_bf16 v[50:53], v[174:177], v[182:185], v[50:53]
	v_mfma_f32_16x16x32_bf16 v[38:41], v[166:169], v[190:193], v[38:41]
	v_mfma_f32_16x16x32_bf16 v[34:37], v[174:177], v[190:193], v[34:37]
	v_mfma_f32_16x16x32_bf16 v[22:25], v[166:169], v[208:211], v[22:25]
	v_mfma_f32_16x16x32_bf16 v[18:21], v[174:177], v[208:211], v[18:21]
	v_mfma_f32_16x16x32_bf16 v[6:9], v[166:169], v[216:219], v[6:9]
	v_mfma_f32_16x16x32_bf16 v[2:5], v[174:177], v[216:219], v[2:5]
	s_barrier
	s_add_i32 s41, s41, 2
	s_add_u32 s39, s39, 0x100
	s_addc_u32 s40, s40, 0
	s_add_u32 s58, s58, 0x100
	s_addc_u32 s59, s59, 0
	s_cmp_gt_u32 s41, 13
	s_cbranch_scc0 .LBB0_647
	s_and_b64 vcc, exec, s[4:5]
	s_cbranch_vccz .LBB0_650
	s_barrier
